# K-loop blocks: vmcnt and lgkmcnt waits before the barrier merged into one s_waitcnt and the redundant wait after the barrier dropped
# speedup vs baseline: 1.0037x; 1.0012x over previous
; #define PG8_STAGE(bufoff, gbase, voff) do { _Pragma("unroll") for (int _i = 0; _i < 2; ++_i) \
;         __builtin_amdgcn_global_load_lds((const unsigned*)((const char*)(gbase) + (voff)[_i]), (PG8_LAS unsigned*)(lds + (bufoff) + ldsw + _i * 8192), 16, 0, 0); } while (0)
; #define PG8_LDA(dst, b, h) do { _Pragma("unroll") for (int m = 0; m < 4; ++m) _Pragma("unroll") for (int k = 0; k < 2; ++k) dst[m][k] = *(const PG8_LAS bf16x8*)(lds + PG8_SA(b, h) + aoff + m * 2048 + k * 1024); } while (0)
; #define PG8_LDB(dst, b, h) do { _Pragma("unroll") for (int n = 0; n < 2; ++n) _Pragma("unroll") for (int k = 0; k < 2; ++k) dst[n][k] = *(const PG8_LAS bf16x8*)(lds + PG8_SB(b, h) + boff + n * 2048 + k * 1024); } while (0)
; #define PG8_MMA(ai, bj, At, Bt) do { __builtin_amdgcn_s_setprio(1); _Pragma("unroll") for (int m = 0; m < 4; ++m) _Pragma("unroll") for (int n = 0; n < 2; ++n) _Pragma("unroll") for (int k = 0; k < 2; ++k) \
;         acc[ai][bj][m][n] = __builtin_amdgcn_mfma_f32_16x16x32_bf16(Bt[n][k], At[m][k], acc[ai][bj][m][n], 0, 0, 0); __builtin_amdgcn_s_setprio(0); } while (0)
; template <class Epi, class Sched, bool ALIGN_EPI = false, bool SP2 = false>
; __device__ __forceinline__ void gemm_phase(PG8_LAS unsigned char* lds, const Gemm g, const Sched& S, const Epi& E) {
;     ...
;         for (int t = 0; t < ntc; t += 2) {
;             if constexpr (Epi::MID) { if (ntc == nt && t == (nt >> 1)) E.mid(acc, cur, wr, wc, fr, fq); }
;             const bool last = (t == ntc - 2);
;             const char* a1 = cA + (size_t)(t + 1) * kstep;
;             const char* a2 = last ? nA : cA + (size_t)(t + 2) * kstep; const char* b2 = last ? nB : cB + (size_t)(t + 2) * kstep;
;             const char* a3 = a2 + kstep; const char* b3 = b2 + kstep;
;             if (last && has_next) S.a_ready(nxt);
;             if constexpr (SP2) {
;             PG8_LDB(B0, 0, 0); PG8_LDB(B1, 0, 1); PG8_SCHED; PG8_LDA(At, 0, 0); PG8_STAGE(PG8_SA(1, 1), a1 + hstep, voffA);
;             PG8_WAIT_V(8); PG8_WAIT_L(0); PG8_BAR; PG8_MMA(0, 0, At, B0); PG8_MMA(0, 1, At, B1); PG8_BAR; PG8_SCHED;
;             PG8_LDA(At, 0, 1); PG8_STAGE(PG8_SB(0, 0), b2, voffB); PG8_STAGE(PG8_SB(0, 1), b2 + hstep, voffB); PG8_STAGE(PG8_SA(0, 0), a2, voffA);
;             PG8_WAIT_V(8); PG8_WAIT_L(0); PG8_BAR; PG8_MMA(1, 0, At, B0); PG8_MMA(1, 1, At, B1); PG8_BAR; PG8_SCHED;
.LBB0_366:
	ds_read_b128 v[130:133], v228
	ds_read_b128 v[134:137], v228 offset:1024
	ds_read_b128 v[138:141], v228 offset:2048
	ds_read_b128 v[170:173], v228 offset:3072
	ds_read_b128 v[174:177], v229
	ds_read_b128 v[178:181], v229 offset:1024
	ds_read_b128 v[182:185], v229 offset:2048
	ds_read_b128 v[186:189], v229 offset:3072
	s_add_u32 s12, s10, 0xfff00080
	s_addc_u32 s13, s11, -1
	s_cmp_eq_u32 s80, 60
	s_cselect_b32 s15, s0, s13
	s_cselect_b32 s14, s1, s12
	s_cselect_b32 s13, s61, s77
	s_cselect_b32 s12, s69, s71
	s_add_i32 m0, s79, 0xc000
	ds_read_b128 v[190:193], v230
	ds_read_b128 v[194:197], v230 offset:1024
	ds_read_b128 v[198:201], v230 offset:2048
	ds_read_b128 v[202:205], v230 offset:3072
	ds_read_b128 v[206:209], v230 offset:4096
	ds_read_b128 v[210:213], v230 offset:5120
	ds_read_b128 v[214:217], v230 offset:6144
	ds_read_b128 v[218:221], v230 offset:7168
	global_load_lds_dwordx4 v164, s[10:11]
	s_add_i32 m0, s79, 0xe000
	s_nop 0
	global_load_lds_dwordx4 v166, s[10:11]
	s_waitcnt vmcnt(8) lgkmcnt(0)
	s_barrier
	v_mfma_f32_16x16x32_bf16 v[126:129], v[130:133], v[190:193], v[126:129]
	v_mfma_f32_16x16x32_bf16 v[126:129], v[134:137], v[194:197], v[126:129]
	v_mfma_f32_16x16x32_bf16 v[122:125], v[138:141], v[190:193], v[122:125]
	v_mfma_f32_16x16x32_bf16 v[122:125], v[170:173], v[194:197], v[122:125]
	v_mfma_f32_16x16x32_bf16 v[106:109], v[138:141], v[198:201], v[106:109]
	v_mfma_f32_16x16x32_bf16 v[106:109], v[170:173], v[202:205], v[106:109]
	v_mfma_f32_16x16x32_bf16 v[110:113], v[130:133], v[198:201], v[110:113]
	v_mfma_f32_16x16x32_bf16 v[110:113], v[134:137], v[202:205], v[110:113]
	v_mfma_f32_16x16x32_bf16 v[94:97], v[130:133], v[206:209], v[94:97]
	v_mfma_f32_16x16x32_bf16 v[94:97], v[134:137], v[210:213], v[94:97]
	v_mfma_f32_16x16x32_bf16 v[90:93], v[138:141], v[206:209], v[90:93]
	v_mfma_f32_16x16x32_bf16 v[90:93], v[170:173], v[210:213], v[90:93]
	v_mfma_f32_16x16x32_bf16 v[74:77], v[138:141], v[214:217], v[74:77]
	v_mfma_f32_16x16x32_bf16 v[74:77], v[170:173], v[218:221], v[74:77]
	v_mfma_f32_16x16x32_bf16 v[78:81], v[130:133], v[214:217], v[78:81]
	v_mfma_f32_16x16x32_bf16 v[78:81], v[134:137], v[218:221], v[78:81]
	v_mfma_f32_16x16x32_bf16 v[118:121], v[174:177], v[190:193], v[118:121]
	v_mfma_f32_16x16x32_bf16 v[118:121], v[178:181], v[194:197], v[118:121]
	v_mfma_f32_16x16x32_bf16 v[114:117], v[182:185], v[190:193], v[114:117]
	v_mfma_f32_16x16x32_bf16 v[114:117], v[186:189], v[194:197], v[114:117]
	v_mfma_f32_16x16x32_bf16 v[98:101], v[182:185], v[198:201], v[98:101]
	v_mfma_f32_16x16x32_bf16 v[98:101], v[186:189], v[202:205], v[98:101]
	v_mfma_f32_16x16x32_bf16 v[102:105], v[174:177], v[198:201], v[102:105]
	v_mfma_f32_16x16x32_bf16 v[102:105], v[178:181], v[202:205], v[102:105]
	v_mfma_f32_16x16x32_bf16 v[86:89], v[174:177], v[206:209], v[86:89]
	v_mfma_f32_16x16x32_bf16 v[86:89], v[178:181], v[210:213], v[86:89]
	v_mfma_f32_16x16x32_bf16 v[82:85], v[182:185], v[206:209], v[82:85]
	v_mfma_f32_16x16x32_bf16 v[82:85], v[186:189], v[210:213], v[82:85]
	v_mfma_f32_16x16x32_bf16 v[66:69], v[182:185], v[214:217], v[66:69]
	v_mfma_f32_16x16x32_bf16 v[66:69], v[186:189], v[218:221], v[66:69]
	v_mfma_f32_16x16x32_bf16 v[70:73], v[174:177], v[214:217], v[70:73]
	v_mfma_f32_16x16x32_bf16 v[70:73], v[178:181], v[218:221], v[70:73]
	s_barrier
	s_add_i32 s81, s63, s67
	s_mov_b32 m0, s81
	ds_read_b128 v[190:193], v230 offset:16384
	ds_read_b128 v[194:197], v230 offset:17408
	ds_read_b128 v[198:201], v230 offset:18432
	ds_read_b128 v[202:205], v230 offset:19456
	ds_read_b128 v[206:209], v230 offset:20480
	ds_read_b128 v[210:213], v230 offset:21504
	ds_read_b128 v[214:217], v230 offset:22528
	ds_read_b128 v[218:221], v230 offset:23552
	global_load_lds_dwordx4 v144, s[12:13]
	s_add_i32 m0, s81, 0x2000
	s_add_u32 s82, s12, 0x100000
	s_addc_u32 s83, s13, 0
	s_add_i32 s81, s94, s67
	global_load_lds_dwordx4 v148, s[12:13]
	s_mov_b32 m0, s81
	s_nop 0
	global_load_lds_dwordx4 v144, s[82:83]
	s_add_i32 m0, s81, 0x2000
	s_nop 0
	global_load_lds_dwordx4 v148, s[82:83]
	s_mov_b32 m0, s79
	s_nop 0
	global_load_lds_dwordx4 v142, s[14:15]
	s_mov_b32 m0, s88
	s_nop 0
	global_load_lds_dwordx4 v146, s[14:15]
	s_waitcnt vmcnt(8) lgkmcnt(0)
	s_barrier
	v_mfma_f32_16x16x32_bf16 v[62:65], v[130:133], v[190:193], v[62:65]
	v_mfma_f32_16x16x32_bf16 v[62:65], v[134:137], v[194:197], v[62:65]
	v_mfma_f32_16x16x32_bf16 v[58:61], v[138:141], v[190:193], v[58:61]
	v_mfma_f32_16x16x32_bf16 v[58:61], v[170:173], v[194:197], v[58:61]
	v_mfma_f32_16x16x32_bf16 v[42:45], v[138:141], v[198:201], v[42:45]
	v_mfma_f32_16x16x32_bf16 v[42:45], v[170:173], v[202:205], v[42:45]
	v_mfma_f32_16x16x32_bf16 v[46:49], v[130:133], v[198:201], v[46:49]
	v_mfma_f32_16x16x32_bf16 v[46:49], v[134:137], v[202:205], v[46:49]
	v_mfma_f32_16x16x32_bf16 v[30:33], v[130:133], v[206:209], v[30:33]
	v_mfma_f32_16x16x32_bf16 v[30:33], v[134:137], v[210:213], v[30:33]
	v_mfma_f32_16x16x32_bf16 v[26:29], v[138:141], v[206:209], v[26:29]
	v_mfma_f32_16x16x32_bf16 v[26:29], v[170:173], v[210:213], v[26:29]
	v_mfma_f32_16x16x32_bf16 v[10:13], v[138:141], v[214:217], v[10:13]
	v_mfma_f32_16x16x32_bf16 v[10:13], v[170:173], v[218:221], v[10:13]
	v_mfma_f32_16x16x32_bf16 v[14:17], v[130:133], v[214:217], v[14:17]
	v_mfma_f32_16x16x32_bf16 v[14:17], v[134:137], v[218:221], v[14:17]
	v_mfma_f32_16x16x32_bf16 v[54:57], v[174:177], v[190:193], v[54:57]
	v_mfma_f32_16x16x32_bf16 v[54:57], v[178:181], v[194:197], v[54:57]
	v_mfma_f32_16x16x32_bf16 v[50:53], v[182:185], v[190:193], v[50:53]
	v_mfma_f32_16x16x32_bf16 v[50:53], v[186:189], v[194:197], v[50:53]
	v_mfma_f32_16x16x32_bf16 v[34:37], v[182:185], v[198:201], v[34:37]
	v_mfma_f32_16x16x32_bf16 v[34:37], v[186:189], v[202:205], v[34:37]
	v_mfma_f32_16x16x32_bf16 v[38:41], v[174:177], v[198:201], v[38:41]
	v_mfma_f32_16x16x32_bf16 v[38:41], v[178:181], v[202:205], v[38:41]
	v_mfma_f32_16x16x32_bf16 v[22:25], v[174:177], v[206:209], v[22:25]
	v_mfma_f32_16x16x32_bf16 v[22:25], v[178:181], v[210:213], v[22:25]
	v_mfma_f32_16x16x32_bf16 v[18:21], v[182:185], v[206:209], v[18:21]
	v_mfma_f32_16x16x32_bf16 v[18:21], v[186:189], v[210:213], v[18:21]
	v_mfma_f32_16x16x32_bf16 v[2:5], v[182:185], v[214:217], v[2:5]
	v_mfma_f32_16x16x32_bf16 v[2:5], v[186:189], v[218:221], v[2:5]
	v_mfma_f32_16x16x32_bf16 v[6:9], v[174:177], v[214:217], v[6:9]
	v_mfma_f32_16x16x32_bf16 v[6:9], v[178:181], v[218:221], v[6:9]
	s_barrier
; #define PG8_STAGE(bufoff, gbase, voff) do { _Pragma("unroll") for (int _i = 0; _i < 2; ++_i) \
;         __builtin_amdgcn_global_load_lds((const unsigned*)((const char*)(gbase) + (voff)[_i]), (PG8_LAS unsigned*)(lds + (bufoff) + ldsw + _i * 8192), 16, 0, 0); } while (0)
; #define PG8_LDA(dst, b, h) do { _Pragma("unroll") for (int m = 0; m < 4; ++m) _Pragma("unroll") for (int k = 0; k < 2; ++k) dst[m][k] = *(const PG8_LAS bf16x8*)(lds + PG8_SA(b, h) + aoff + m * 2048 + k * 1024); } while (0)
; #define PG8_LDB(dst, b, h) do { _Pragma("unroll") for (int n = 0; n < 2; ++n) _Pragma("unroll") for (int k = 0; k < 2; ++k) dst[n][k] = *(const PG8_LAS bf16x8*)(lds + PG8_SB(b, h) + boff + n * 2048 + k * 1024); } while (0)
; #define PG8_MMA(ai, bj, At, Bt) do { __builtin_amdgcn_s_setprio(1); _Pragma("unroll") for (int m = 0; m < 4; ++m) _Pragma("unroll") for (int n = 0; n < 2; ++n) _Pragma("unroll") for (int k = 0; k < 2; ++k) \
;         acc[ai][bj][m][n] = __builtin_amdgcn_mfma_f32_16x16x32_bf16(Bt[n][k], At[m][k], acc[ai][bj][m][n], 0, 0, 0); __builtin_amdgcn_s_setprio(0); } while (0)
; #define PG8_WAIT_V(n) asm volatile("s_waitcnt vmcnt(" #n ")" ::: "memory")
; #define PG8_WAIT_L(n) asm volatile("s_waitcnt lgkmcnt(" #n ")" ::: "memory")
; #define PG8_BAR __builtin_amdgcn_s_barrier()
; #define PG8_SCHED __builtin_amdgcn_sched_barrier(0)
; template <class Epi, class Sched, bool ALIGN_EPI = false, bool SP2 = false>
; __device__ __forceinline__ void gemm_phase(PG8_LAS unsigned char* lds, const Gemm g, const Sched& S, const Epi& E) {
;     ...
;         for (int t = 0; t < ntc; t += 2) {
;     ...
;             PG8_LDB(B0, 1, 0); PG8_LDB(B1, 1, 1); PG8_SCHED; PG8_LDA(At, 1, 0); PG8_STAGE(PG8_SA(0, 1), a2 + hstep, voffA);
;             PG8_WAIT_V(8); PG8_WAIT_L(0); PG8_BAR; PG8_MMA(0, 0, At, B0); PG8_MMA(0, 1, At, B1); PG8_BAR; PG8_SCHED;
;             PG8_LDA(At, 1, 1); PG8_STAGE(PG8_SB(1, 0), b3, voffB); PG8_STAGE(PG8_SB(1, 1), b3 + hstep, voffB); PG8_STAGE(PG8_SA(1, 0), a3, voffA);
;             PG8_WAIT_V(8); PG8_WAIT_L(0); PG8_BAR; PG8_MMA(1, 0, At, B0); PG8_MMA(1, 1, At, B1); PG8_BAR; PG8_SCHED;
	s_add_i32 s81, 0, 0x18000
	v_add_u32_e32 v150, s81, v153
	s_add_i32 s82, 0, 0x1c000
	ds_read_b128 v[130:133], v150
	ds_read_b128 v[134:137], v150 offset:1024
	ds_read_b128 v[138:141], v150 offset:2048
	ds_read_b128 v[170:173], v150 offset:3072
	v_add_u32_e32 v150, s82, v153
	ds_read_b128 v[174:177], v150
	ds_read_b128 v[178:181], v150 offset:1024
	ds_read_b128 v[182:185], v150 offset:2048
	ds_read_b128 v[186:189], v150 offset:3072
	s_add_u32 s14, s14, 0x100000
	s_addc_u32 s15, s15, 0
	s_mov_b32 m0, s89
	ds_read_b128 v[190:193], v230 offset:32768
	ds_read_b128 v[194:197], v230 offset:33792
	ds_read_b128 v[198:201], v230 offset:34816
	ds_read_b128 v[202:205], v230 offset:35840
	ds_read_b128 v[206:209], v230 offset:36864
	ds_read_b128 v[210:213], v230 offset:37888
	ds_read_b128 v[214:217], v230 offset:38912
	ds_read_b128 v[218:221], v230 offset:39936
	global_load_lds_dwordx4 v142, s[14:15]
	s_mov_b32 m0, s90
	s_nop 0
	global_load_lds_dwordx4 v146, s[14:15]
	s_waitcnt vmcnt(8) lgkmcnt(0)
	s_barrier
	v_mfma_f32_16x16x32_bf16 v[126:129], v[130:133], v[190:193], v[126:129]
	v_mfma_f32_16x16x32_bf16 v[126:129], v[134:137], v[194:197], v[126:129]
	v_mfma_f32_16x16x32_bf16 v[122:125], v[138:141], v[190:193], v[122:125]
	v_mfma_f32_16x16x32_bf16 v[122:125], v[170:173], v[194:197], v[122:125]
	v_mfma_f32_16x16x32_bf16 v[106:109], v[138:141], v[198:201], v[106:109]
	v_mfma_f32_16x16x32_bf16 v[106:109], v[170:173], v[202:205], v[106:109]
	v_mfma_f32_16x16x32_bf16 v[110:113], v[130:133], v[198:201], v[110:113]
	v_mfma_f32_16x16x32_bf16 v[110:113], v[134:137], v[202:205], v[110:113]
	v_mfma_f32_16x16x32_bf16 v[94:97], v[130:133], v[206:209], v[94:97]
	v_mfma_f32_16x16x32_bf16 v[94:97], v[134:137], v[210:213], v[94:97]
	v_mfma_f32_16x16x32_bf16 v[90:93], v[138:141], v[206:209], v[90:93]
	v_mfma_f32_16x16x32_bf16 v[90:93], v[170:173], v[210:213], v[90:93]
	v_mfma_f32_16x16x32_bf16 v[74:77], v[138:141], v[214:217], v[74:77]
	v_mfma_f32_16x16x32_bf16 v[74:77], v[170:173], v[218:221], v[74:77]
	v_mfma_f32_16x16x32_bf16 v[78:81], v[130:133], v[214:217], v[78:81]
	v_mfma_f32_16x16x32_bf16 v[78:81], v[134:137], v[218:221], v[78:81]
	v_mfma_f32_16x16x32_bf16 v[118:121], v[174:177], v[190:193], v[118:121]
	v_mfma_f32_16x16x32_bf16 v[118:121], v[178:181], v[194:197], v[118:121]
	v_mfma_f32_16x16x32_bf16 v[114:117], v[182:185], v[190:193], v[114:117]
	v_mfma_f32_16x16x32_bf16 v[114:117], v[186:189], v[194:197], v[114:117]
	v_mfma_f32_16x16x32_bf16 v[98:101], v[182:185], v[198:201], v[98:101]
	v_mfma_f32_16x16x32_bf16 v[98:101], v[186:189], v[202:205], v[98:101]
	v_mfma_f32_16x16x32_bf16 v[102:105], v[174:177], v[198:201], v[102:105]
	v_mfma_f32_16x16x32_bf16 v[102:105], v[178:181], v[202:205], v[102:105]
	v_mfma_f32_16x16x32_bf16 v[86:89], v[174:177], v[206:209], v[86:89]
	v_mfma_f32_16x16x32_bf16 v[86:89], v[178:181], v[210:213], v[86:89]
	v_mfma_f32_16x16x32_bf16 v[82:85], v[182:185], v[206:209], v[82:85]
	v_mfma_f32_16x16x32_bf16 v[82:85], v[186:189], v[210:213], v[82:85]
	v_mfma_f32_16x16x32_bf16 v[66:69], v[182:185], v[214:217], v[66:69]
	v_mfma_f32_16x16x32_bf16 v[66:69], v[186:189], v[218:221], v[66:69]
	v_mfma_f32_16x16x32_bf16 v[70:73], v[174:177], v[214:217], v[70:73]
	v_mfma_f32_16x16x32_bf16 v[70:73], v[178:181], v[218:221], v[70:73]
	s_barrier
	s_add_u32 s100, s14, 0xfff00080
	s_addc_u32 s101, s15, -1
	s_add_u32 s98, s12, 0x80
	s_addc_u32 s99, s13, 0
	s_add_i32 s14, s81, s67
	s_mov_b32 m0, s14
	ds_read_b128 v[190:193], v230 offset:49152
	ds_read_b128 v[194:197], v230 offset:50176
	ds_read_b128 v[198:201], v230 offset:51200
	ds_read_b128 v[202:205], v230 offset:52224
	ds_read_b128 v[206:209], v230 offset:53248
	ds_read_b128 v[210:213], v230 offset:54272
	ds_read_b128 v[214:217], v230 offset:55296
	ds_read_b128 v[218:221], v230 offset:56320
	global_load_lds_dwordx4 v144, s[98:99]
	s_add_i32 m0, s14, 0x2000
	s_add_u32 s12, s12, 0x100080
	s_addc_u32 s13, s13, 0
	s_add_i32 s14, s82, s67
	global_load_lds_dwordx4 v148, s[98:99]
	s_mov_b32 m0, s14
	s_nop 0
	global_load_lds_dwordx4 v144, s[12:13]
	s_add_i32 m0, s14, 0x2000
	s_nop 0
	global_load_lds_dwordx4 v148, s[12:13]
	s_mov_b32 m0, s93
	s_nop 0
	global_load_lds_dwordx4 v142, s[100:101]
	s_mov_b32 m0, s62
	s_nop 0
	global_load_lds_dwordx4 v146, s[100:101]
	s_waitcnt vmcnt(8) lgkmcnt(0)
	s_barrier
	v_mfma_f32_16x16x32_bf16 v[62:65], v[130:133], v[190:193], v[62:65]
	v_mfma_f32_16x16x32_bf16 v[62:65], v[134:137], v[194:197], v[62:65]
	v_mfma_f32_16x16x32_bf16 v[58:61], v[138:141], v[190:193], v[58:61]
	v_mfma_f32_16x16x32_bf16 v[58:61], v[170:173], v[194:197], v[58:61]
	v_mfma_f32_16x16x32_bf16 v[42:45], v[138:141], v[198:201], v[42:45]
	v_mfma_f32_16x16x32_bf16 v[42:45], v[170:173], v[202:205], v[42:45]
	v_mfma_f32_16x16x32_bf16 v[46:49], v[130:133], v[198:201], v[46:49]
	v_mfma_f32_16x16x32_bf16 v[46:49], v[134:137], v[202:205], v[46:49]
	v_mfma_f32_16x16x32_bf16 v[30:33], v[130:133], v[206:209], v[30:33]
	v_mfma_f32_16x16x32_bf16 v[30:33], v[134:137], v[210:213], v[30:33]
	v_mfma_f32_16x16x32_bf16 v[26:29], v[138:141], v[206:209], v[26:29]
	v_mfma_f32_16x16x32_bf16 v[26:29], v[170:173], v[210:213], v[26:29]
	v_mfma_f32_16x16x32_bf16 v[10:13], v[138:141], v[214:217], v[10:13]
	v_mfma_f32_16x16x32_bf16 v[10:13], v[170:173], v[218:221], v[10:13]
	v_mfma_f32_16x16x32_bf16 v[14:17], v[130:133], v[214:217], v[14:17]
	v_mfma_f32_16x16x32_bf16 v[14:17], v[134:137], v[218:221], v[14:17]
	v_mfma_f32_16x16x32_bf16 v[54:57], v[174:177], v[190:193], v[54:57]
	v_mfma_f32_16x16x32_bf16 v[54:57], v[178:181], v[194:197], v[54:57]
	v_mfma_f32_16x16x32_bf16 v[50:53], v[182:185], v[190:193], v[50:53]
	v_mfma_f32_16x16x32_bf16 v[50:53], v[186:189], v[194:197], v[50:53]
	v_mfma_f32_16x16x32_bf16 v[34:37], v[182:185], v[198:201], v[34:37]
	v_mfma_f32_16x16x32_bf16 v[34:37], v[186:189], v[202:205], v[34:37]
	v_mfma_f32_16x16x32_bf16 v[38:41], v[174:177], v[198:201], v[38:41]
	v_mfma_f32_16x16x32_bf16 v[38:41], v[178:181], v[202:205], v[38:41]
	v_mfma_f32_16x16x32_bf16 v[22:25], v[174:177], v[206:209], v[22:25]
	v_mfma_f32_16x16x32_bf16 v[22:25], v[178:181], v[210:213], v[22:25]
	v_mfma_f32_16x16x32_bf16 v[18:21], v[182:185], v[206:209], v[18:21]
	v_mfma_f32_16x16x32_bf16 v[18:21], v[186:189], v[210:213], v[18:21]
	v_mfma_f32_16x16x32_bf16 v[2:5], v[182:185], v[214:217], v[2:5]
	v_mfma_f32_16x16x32_bf16 v[2:5], v[186:189], v[218:221], v[2:5]
	v_mfma_f32_16x16x32_bf16 v[6:9], v[174:177], v[214:217], v[6:9]
	v_mfma_f32_16x16x32_bf16 v[6:9], v[178:181], v[218:221], v[6:9]
	s_barrier
	s_add_i32 s80, s80, 2
	s_add_u32 s10, s10, 0x100
	s_addc_u32 s11, s11, 0
	s_add_u32 s71, s71, 0x100
	s_addc_u32 s77, s77, 0
	s_cmp_gt_u32 s80, 61
	s_cbranch_scc0 .LBB0_366
	s_and_b64 vcc, exec, s[28:29]
	s_cbranch_vccz .LBB0_369
	s_barrier

; #define PG8_STAGE(bufoff, gbase, voff) do { _Pragma("unroll") for (int _i = 0; _i < 2; ++_i) \
;         __builtin_amdgcn_global_load_lds((const unsigned*)((const char*)(gbase) + (voff)[_i]), (PG8_LAS unsigned*)(lds + (bufoff) + ldsw + _i * 8192), 16, 0, 0); } while (0)
; #define PG8_LDA(dst, b, h) do { _Pragma("unroll") for (int m = 0; m < 4; ++m) _Pragma("unroll") for (int k = 0; k < 2; ++k) dst[m][k] = *(const PG8_LAS bf16x8*)(lds + PG8_SA(b, h) + aoff + m * 2048 + k * 1024); } while (0)
; #define PG8_LDB(dst, b, h) do { _Pragma("unroll") for (int n = 0; n < 2; ++n) _Pragma("unroll") for (int k = 0; k < 2; ++k) dst[n][k] = *(const PG8_LAS bf16x8*)(lds + PG8_SB(b, h) + boff + n * 2048 + k * 1024); } while (0)
; #define PG8_MMA(ai, bj, At, Bt) do { __builtin_amdgcn_s_setprio(1); _Pragma("unroll") for (int m = 0; m < 4; ++m) _Pragma("unroll") for (int n = 0; n < 2; ++n) _Pragma("unroll") for (int k = 0; k < 2; ++k) \
;         acc[ai][bj][m][n] = __builtin_amdgcn_mfma_f32_16x16x32_bf16(Bt[n][k], At[m][k], acc[ai][bj][m][n], 0, 0, 0); __builtin_amdgcn_s_setprio(0); } while (0)
; template <class Epi, class Sched, bool ALIGN_EPI = false, bool SP2 = false>
; __device__ __forceinline__ void gemm_phase(PG8_LAS unsigned char* lds, const Gemm g, const Sched& S, const Epi& E) {
;     ...
;         for (int t = 0; t < ntc; t += 2) {
;             if constexpr (Epi::MID) { if (ntc == nt && t == (nt >> 1)) E.mid(acc, cur, wr, wc, fr, fq); }
;             const bool last = (t == ntc - 2);
;             const char* a1 = cA + (size_t)(t + 1) * kstep;
;             const char* a2 = last ? nA : cA + (size_t)(t + 2) * kstep; const char* b2 = last ? nB : cB + (size_t)(t + 2) * kstep;
;             const char* a3 = a2 + kstep; const char* b3 = b2 + kstep;
;             if (last && has_next) S.a_ready(nxt);
;             if constexpr (SP2) {
;             PG8_LDB(B0, 0, 0); PG8_LDB(B1, 0, 1); PG8_SCHED; PG8_LDA(At, 0, 0); PG8_STAGE(PG8_SA(1, 1), a1 + hstep, voffA);
;             PG8_WAIT_V(8); PG8_WAIT_L(0); PG8_BAR; PG8_MMA(0, 0, At, B0); PG8_MMA(0, 1, At, B1); PG8_BAR; PG8_SCHED;
;             PG8_LDA(At, 0, 1); PG8_STAGE(PG8_SB(0, 0), b2, voffB); PG8_STAGE(PG8_SB(0, 1), b2 + hstep, voffB); PG8_STAGE(PG8_SA(0, 0), a2, voffA);
;             PG8_WAIT_V(8); PG8_WAIT_L(0); PG8_BAR; PG8_MMA(1, 0, At, B0); PG8_MMA(1, 1, At, B1); PG8_BAR; PG8_SCHED;
.LBB0_2487:
	v_add_u32_e32 v3, s67, v183
	s_add_i32 s81, s50, 2
	ds_read_b128 v[154:157], v3
	ds_read_b128 v[158:161], v3 offset:1024
	ds_read_b128 v[162:165], v3 offset:2048
	ds_read_b128 v[166:169], v3 offset:3072
	v_add_u32_e32 v3, s68, v183
	s_add_u32 s51, s42, s46
	ds_read_b128 v[170:173], v3
	ds_read_b128 v[174:177], v3 offset:1024
	ds_read_b128 v[178:181], v3 offset:2048
	ds_read_b128 v[184:187], v3 offset:3072
	s_addc_u32 s52, s43, s47
	s_add_u32 s51, s51, 0x100
	s_addc_u32 s52, s52, 0
	s_add_u32 s82, s79, s46
	s_addc_u32 s83, s80, s47
	s_cmp_eq_u32 s9, s50
	s_cselect_b32 s53, s27, s52
	s_cselect_b32 s52, s35, s51
	s_cselect_b32 s51, s31, s83
	s_cselect_b32 s50, s78, s82
	v_lshl_add_u64 v[4:5], v[150:151], 0, s[46:47]
	s_add_i32 m0, s11, 0xc000
	ds_read_b128 v[188:191], v211
	ds_read_b128 v[192:195], v211 offset:1024
	ds_read_b128 v[196:199], v211 offset:2048
	ds_read_b128 v[200:203], v211 offset:3072
	ds_read_b128 v[204:207], v211 offset:4096
	ds_read_b128 v[212:215], v211 offset:5120
	ds_read_b128 v[216:219], v211 offset:6144
	ds_read_b128 v[220:223], v211 offset:7168
	global_load_lds_dwordx4 v[4:5], off
	v_lshl_add_u64 v[4:5], v[152:153], 0, s[46:47]
	s_add_i32 m0, s11, 0xe000
	s_nop 0
	global_load_lds_dwordx4 v[4:5], off
	s_waitcnt vmcnt(8) lgkmcnt(0)
	s_barrier
	v_mfma_f32_16x16x32_bf16 v[130:133], v[154:157], v[188:191], v[130:133]
	v_mfma_f32_16x16x32_bf16 v[130:133], v[158:161], v[192:195], v[130:133]
	v_mfma_f32_16x16x32_bf16 v[126:129], v[162:165], v[188:191], v[126:129]
	v_mfma_f32_16x16x32_bf16 v[126:129], v[166:169], v[192:195], v[126:129]
	v_mfma_f32_16x16x32_bf16 v[110:113], v[162:165], v[196:199], v[110:113]
	v_mfma_f32_16x16x32_bf16 v[110:113], v[166:169], v[200:203], v[110:113]
	v_mfma_f32_16x16x32_bf16 v[114:117], v[154:157], v[196:199], v[114:117]
	v_mfma_f32_16x16x32_bf16 v[114:117], v[158:161], v[200:203], v[114:117]
	v_mfma_f32_16x16x32_bf16 v[98:101], v[154:157], v[204:207], v[98:101]
	v_mfma_f32_16x16x32_bf16 v[98:101], v[158:161], v[212:215], v[98:101]
	v_mfma_f32_16x16x32_bf16 v[94:97], v[162:165], v[204:207], v[94:97]
	v_mfma_f32_16x16x32_bf16 v[94:97], v[166:169], v[212:215], v[94:97]
	v_mfma_f32_16x16x32_bf16 v[78:81], v[162:165], v[216:219], v[78:81]
	v_mfma_f32_16x16x32_bf16 v[78:81], v[166:169], v[220:223], v[78:81]
	v_mfma_f32_16x16x32_bf16 v[82:85], v[154:157], v[216:219], v[82:85]
	v_mfma_f32_16x16x32_bf16 v[82:85], v[158:161], v[220:223], v[82:85]
	v_mfma_f32_16x16x32_bf16 v[122:125], v[170:173], v[188:191], v[122:125]
	v_mfma_f32_16x16x32_bf16 v[122:125], v[174:177], v[192:195], v[122:125]
	v_mfma_f32_16x16x32_bf16 v[118:121], v[178:181], v[188:191], v[118:121]
	v_mfma_f32_16x16x32_bf16 v[118:121], v[184:187], v[192:195], v[118:121]
	v_mfma_f32_16x16x32_bf16 v[102:105], v[178:181], v[196:199], v[102:105]
	v_mfma_f32_16x16x32_bf16 v[102:105], v[184:187], v[200:203], v[102:105]
	v_mfma_f32_16x16x32_bf16 v[106:109], v[170:173], v[196:199], v[106:109]
	v_mfma_f32_16x16x32_bf16 v[106:109], v[174:177], v[200:203], v[106:109]
	v_mfma_f32_16x16x32_bf16 v[90:93], v[170:173], v[204:207], v[90:93]
	v_mfma_f32_16x16x32_bf16 v[90:93], v[174:177], v[212:215], v[90:93]
	v_mfma_f32_16x16x32_bf16 v[86:89], v[178:181], v[204:207], v[86:89]
	v_mfma_f32_16x16x32_bf16 v[86:89], v[184:187], v[212:215], v[86:89]
	v_mfma_f32_16x16x32_bf16 v[70:73], v[178:181], v[216:219], v[70:73]
	v_mfma_f32_16x16x32_bf16 v[70:73], v[184:187], v[220:223], v[70:73]
	v_mfma_f32_16x16x32_bf16 v[74:77], v[170:173], v[216:219], v[74:77]
	v_mfma_f32_16x16x32_bf16 v[74:77], v[174:177], v[220:223], v[74:77]
	s_barrier
	s_add_i32 s82, s67, s55
	s_mov_b32 m0, s82
	ds_read_b128 v[188:191], v211 offset:16384
	ds_read_b128 v[192:195], v211 offset:17408
	ds_read_b128 v[196:199], v211 offset:18432
	ds_read_b128 v[200:203], v211 offset:19456
	ds_read_b128 v[204:207], v211 offset:20480
	ds_read_b128 v[212:215], v211 offset:21504
	ds_read_b128 v[216:219], v211 offset:22528
	ds_read_b128 v[220:223], v211 offset:23552
	global_load_lds_dwordx4 v134, s[50:51]
	s_add_i32 m0, s82, 0x2000
	s_add_u32 s82, s50, 0x100000
	s_addc_u32 s83, s51, 0
	s_add_i32 s84, s68, s55
	global_load_lds_dwordx4 v136, s[50:51]
	s_mov_b32 m0, s84
	s_nop 0
	global_load_lds_dwordx4 v134, s[82:83]
	s_add_i32 m0, s84, 0x2000
	s_nop 0
	global_load_lds_dwordx4 v136, s[82:83]
	s_mov_b32 m0, s11
	s_nop 0
	global_load_lds_dwordx4 v134, s[52:53]
	s_mov_b32 m0, s57
	s_nop 0
	global_load_lds_dwordx4 v136, s[52:53]
	s_waitcnt vmcnt(8) lgkmcnt(0)
	s_barrier
	v_mfma_f32_16x16x32_bf16 v[66:69], v[154:157], v[188:191], v[66:69]
	v_mfma_f32_16x16x32_bf16 v[66:69], v[158:161], v[192:195], v[66:69]
	v_mfma_f32_16x16x32_bf16 v[62:65], v[162:165], v[188:191], v[62:65]
	v_mfma_f32_16x16x32_bf16 v[62:65], v[166:169], v[192:195], v[62:65]
	v_mfma_f32_16x16x32_bf16 v[46:49], v[162:165], v[196:199], v[46:49]
	v_mfma_f32_16x16x32_bf16 v[46:49], v[166:169], v[200:203], v[46:49]
	v_mfma_f32_16x16x32_bf16 v[50:53], v[154:157], v[196:199], v[50:53]
	v_mfma_f32_16x16x32_bf16 v[50:53], v[158:161], v[200:203], v[50:53]
	v_mfma_f32_16x16x32_bf16 v[34:37], v[154:157], v[204:207], v[34:37]
	v_mfma_f32_16x16x32_bf16 v[34:37], v[158:161], v[212:215], v[34:37]
	v_mfma_f32_16x16x32_bf16 v[30:33], v[162:165], v[204:207], v[30:33]
	v_mfma_f32_16x16x32_bf16 v[30:33], v[166:169], v[212:215], v[30:33]
	v_mfma_f32_16x16x32_bf16 v[14:17], v[162:165], v[216:219], v[14:17]
	v_mfma_f32_16x16x32_bf16 v[14:17], v[166:169], v[220:223], v[14:17]
	v_mfma_f32_16x16x32_bf16 v[18:21], v[154:157], v[216:219], v[18:21]
	v_mfma_f32_16x16x32_bf16 v[18:21], v[158:161], v[220:223], v[18:21]
	v_mfma_f32_16x16x32_bf16 v[58:61], v[170:173], v[188:191], v[58:61]
	v_mfma_f32_16x16x32_bf16 v[58:61], v[174:177], v[192:195], v[58:61]
	v_mfma_f32_16x16x32_bf16 v[54:57], v[178:181], v[188:191], v[54:57]
	v_mfma_f32_16x16x32_bf16 v[54:57], v[184:187], v[192:195], v[54:57]
	v_mfma_f32_16x16x32_bf16 v[42:45], v[170:173], v[196:199], v[42:45]
	v_mfma_f32_16x16x32_bf16 v[42:45], v[174:177], v[200:203], v[42:45]
	v_mfma_f32_16x16x32_bf16 v[38:41], v[178:181], v[196:199], v[38:41]
	v_mfma_f32_16x16x32_bf16 v[38:41], v[184:187], v[200:203], v[38:41]
	v_mfma_f32_16x16x32_bf16 v[26:29], v[170:173], v[204:207], v[26:29]
	v_mfma_f32_16x16x32_bf16 v[26:29], v[174:177], v[212:215], v[26:29]
	v_mfma_f32_16x16x32_bf16 v[22:25], v[178:181], v[204:207], v[22:25]
	v_mfma_f32_16x16x32_bf16 v[22:25], v[184:187], v[212:215], v[22:25]
	v_mfma_f32_16x16x32_bf16 v[10:13], v[170:173], v[216:219], v[10:13]
	v_mfma_f32_16x16x32_bf16 v[10:13], v[174:177], v[220:223], v[10:13]
	v_mfma_f32_16x16x32_bf16 v[4:7], v[178:181], v[216:219], v[6:9]
	v_mfma_f32_16x16x32_bf16 v[4:7], v[184:187], v[220:223], v[4:7]
	s_barrier
; #define PG8_STAGE(bufoff, gbase, voff) do { _Pragma("unroll") for (int _i = 0; _i < 2; ++_i) \
;         __builtin_amdgcn_global_load_lds((const unsigned*)((const char*)(gbase) + (voff)[_i]), (PG8_LAS unsigned*)(lds + (bufoff) + ldsw + _i * 8192), 16, 0, 0); } while (0)
; #define PG8_LDA(dst, b, h) do { _Pragma("unroll") for (int m = 0; m < 4; ++m) _Pragma("unroll") for (int k = 0; k < 2; ++k) dst[m][k] = *(const PG8_LAS bf16x8*)(lds + PG8_SA(b, h) + aoff + m * 2048 + k * 1024); } while (0)
; #define PG8_LDB(dst, b, h) do { _Pragma("unroll") for (int n = 0; n < 2; ++n) _Pragma("unroll") for (int k = 0; k < 2; ++k) dst[n][k] = *(const PG8_LAS bf16x8*)(lds + PG8_SB(b, h) + boff + n * 2048 + k * 1024); } while (0)
; #define PG8_MMA(ai, bj, At, Bt) do { __builtin_amdgcn_s_setprio(1); _Pragma("unroll") for (int m = 0; m < 4; ++m) _Pragma("unroll") for (int n = 0; n < 2; ++n) _Pragma("unroll") for (int k = 0; k < 2; ++k) \
;         acc[ai][bj][m][n] = __builtin_amdgcn_mfma_f32_16x16x32_bf16(Bt[n][k], At[m][k], acc[ai][bj][m][n], 0, 0, 0); __builtin_amdgcn_s_setprio(0); } while (0)
; #define PG8_WAIT_V(n) asm volatile("s_waitcnt vmcnt(" #n ")" ::: "memory")
; #define PG8_WAIT_L(n) asm volatile("s_waitcnt lgkmcnt(" #n ")" ::: "memory")
; #define PG8_BAR __builtin_amdgcn_s_barrier()
; #define PG8_SCHED __builtin_amdgcn_sched_barrier(0)
; template <class Epi, class Sched, bool ALIGN_EPI = false, bool SP2 = false>
; __device__ __forceinline__ void gemm_phase(PG8_LAS unsigned char* lds, const Gemm g, const Sched& S, const Epi& E) {
;     ...
;         for (int t = 0; t < ntc; t += 2) {
;     ...
;             PG8_LDB(B0, 1, 0); PG8_LDB(B1, 1, 1); PG8_SCHED; PG8_LDA(At, 1, 0); PG8_STAGE(PG8_SA(0, 1), a2 + hstep, voffA);
;             PG8_WAIT_V(8); PG8_WAIT_L(0); PG8_BAR; PG8_MMA(0, 0, At, B0); PG8_MMA(0, 1, At, B1); PG8_BAR; PG8_SCHED;
;             PG8_LDA(At, 1, 1); PG8_STAGE(PG8_SB(1, 0), b3, voffB); PG8_STAGE(PG8_SB(1, 1), b3 + hstep, voffB); PG8_STAGE(PG8_SA(1, 0), a3, voffA);
;             PG8_WAIT_V(8); PG8_WAIT_L(0); PG8_BAR; PG8_MMA(1, 0, At, B0); PG8_MMA(1, 1, At, B1); PG8_BAR; PG8_SCHED;
	s_add_i32 s82, 0, 0x18000
	v_add_u32_e32 v3, s82, v183
	s_add_i32 s83, 0, 0x1c000
	ds_read_b128 v[154:157], v3
	ds_read_b128 v[158:161], v3 offset:1024
	ds_read_b128 v[162:165], v3 offset:2048
	ds_read_b128 v[166:169], v3 offset:3072
	v_add_u32_e32 v3, s83, v183
	ds_read_b128 v[170:173], v3
	ds_read_b128 v[174:177], v3 offset:1024
	ds_read_b128 v[178:181], v3 offset:2048
	ds_read_b128 v[184:187], v3 offset:3072
	s_add_u32 s52, s52, 0x100000
	s_addc_u32 s53, s53, 0
	s_mov_b32 m0, s60
	ds_read_b128 v[188:191], v211 offset:32768
	ds_read_b128 v[192:195], v211 offset:33792
	ds_read_b128 v[196:199], v211 offset:34816
	ds_read_b128 v[200:203], v211 offset:35840
	ds_read_b128 v[204:207], v211 offset:36864
	ds_read_b128 v[212:215], v211 offset:37888
	ds_read_b128 v[216:219], v211 offset:38912
	ds_read_b128 v[220:223], v211 offset:39936
	global_load_lds_dwordx4 v134, s[52:53]
	s_mov_b32 m0, s61
	s_nop 0
	global_load_lds_dwordx4 v136, s[52:53]
	s_waitcnt vmcnt(8) lgkmcnt(0)
	s_barrier
	v_mfma_f32_16x16x32_bf16 v[130:133], v[154:157], v[188:191], v[130:133]
	v_mfma_f32_16x16x32_bf16 v[130:133], v[158:161], v[192:195], v[130:133]
	v_mfma_f32_16x16x32_bf16 v[126:129], v[162:165], v[188:191], v[126:129]
	v_mfma_f32_16x16x32_bf16 v[126:129], v[166:169], v[192:195], v[126:129]
	v_mfma_f32_16x16x32_bf16 v[110:113], v[162:165], v[196:199], v[110:113]
	v_mfma_f32_16x16x32_bf16 v[110:113], v[166:169], v[200:203], v[110:113]
	v_mfma_f32_16x16x32_bf16 v[114:117], v[154:157], v[196:199], v[114:117]
	v_mfma_f32_16x16x32_bf16 v[114:117], v[158:161], v[200:203], v[114:117]
	v_mfma_f32_16x16x32_bf16 v[98:101], v[154:157], v[204:207], v[98:101]
	v_mfma_f32_16x16x32_bf16 v[98:101], v[158:161], v[212:215], v[98:101]
	v_mfma_f32_16x16x32_bf16 v[94:97], v[162:165], v[204:207], v[94:97]
	v_mfma_f32_16x16x32_bf16 v[94:97], v[166:169], v[212:215], v[94:97]
	v_mfma_f32_16x16x32_bf16 v[78:81], v[162:165], v[216:219], v[78:81]
	v_mfma_f32_16x16x32_bf16 v[78:81], v[166:169], v[220:223], v[78:81]
	v_mfma_f32_16x16x32_bf16 v[82:85], v[154:157], v[216:219], v[82:85]
	v_mfma_f32_16x16x32_bf16 v[82:85], v[158:161], v[220:223], v[82:85]
	v_mfma_f32_16x16x32_bf16 v[122:125], v[170:173], v[188:191], v[122:125]
	v_mfma_f32_16x16x32_bf16 v[122:125], v[174:177], v[192:195], v[122:125]
	v_mfma_f32_16x16x32_bf16 v[118:121], v[178:181], v[188:191], v[118:121]
	v_mfma_f32_16x16x32_bf16 v[118:121], v[184:187], v[192:195], v[118:121]
	v_mfma_f32_16x16x32_bf16 v[102:105], v[178:181], v[196:199], v[102:105]
	v_mfma_f32_16x16x32_bf16 v[102:105], v[184:187], v[200:203], v[102:105]
	v_mfma_f32_16x16x32_bf16 v[106:109], v[170:173], v[196:199], v[106:109]
	v_mfma_f32_16x16x32_bf16 v[106:109], v[174:177], v[200:203], v[106:109]
	v_mfma_f32_16x16x32_bf16 v[90:93], v[170:173], v[204:207], v[90:93]
	v_mfma_f32_16x16x32_bf16 v[90:93], v[174:177], v[212:215], v[90:93]
	v_mfma_f32_16x16x32_bf16 v[86:89], v[178:181], v[204:207], v[86:89]
	v_mfma_f32_16x16x32_bf16 v[86:89], v[184:187], v[212:215], v[86:89]
	v_mfma_f32_16x16x32_bf16 v[70:73], v[178:181], v[216:219], v[70:73]
	v_mfma_f32_16x16x32_bf16 v[70:73], v[184:187], v[220:223], v[70:73]
	v_mfma_f32_16x16x32_bf16 v[74:77], v[170:173], v[216:219], v[74:77]
	v_mfma_f32_16x16x32_bf16 v[74:77], v[174:177], v[220:223], v[74:77]
	s_barrier
	s_add_u32 s100, s52, 0xfff00080
	s_addc_u32 s101, s53, -1
	s_add_u32 s98, s50, 0x80
	s_addc_u32 s99, s51, 0
	s_add_i32 s52, s82, s55
	s_mov_b32 m0, s52
	ds_read_b128 v[188:191], v211 offset:49152
	ds_read_b128 v[192:195], v211 offset:50176
	ds_read_b128 v[196:199], v211 offset:51200
	ds_read_b128 v[200:203], v211 offset:52224
	ds_read_b128 v[204:207], v211 offset:53248
	ds_read_b128 v[212:215], v211 offset:54272
	ds_read_b128 v[216:219], v211 offset:55296
	ds_read_b128 v[220:223], v211 offset:56320
	global_load_lds_dwordx4 v134, s[98:99]
	s_add_i32 m0, s52, 0x2000
	s_add_u32 s50, s50, 0x100080
	s_addc_u32 s51, s51, 0
	s_add_i32 s52, s83, s55
	global_load_lds_dwordx4 v136, s[98:99]
	s_mov_b32 m0, s52
	s_nop 0
	global_load_lds_dwordx4 v134, s[50:51]
	s_add_i32 m0, s52, 0x2000
	s_nop 0
	global_load_lds_dwordx4 v136, s[50:51]
	s_mov_b32 m0, s63
	s_nop 0
	global_load_lds_dwordx4 v134, s[100:101]
	s_mov_b32 m0, s64
	s_nop 0
	global_load_lds_dwordx4 v136, s[100:101]
	s_waitcnt vmcnt(8) lgkmcnt(0)
	s_barrier
	v_mfma_f32_16x16x32_bf16 v[66:69], v[154:157], v[188:191], v[66:69]
	v_mfma_f32_16x16x32_bf16 v[66:69], v[158:161], v[192:195], v[66:69]
	v_mfma_f32_16x16x32_bf16 v[62:65], v[162:165], v[188:191], v[62:65]
	v_mfma_f32_16x16x32_bf16 v[62:65], v[166:169], v[192:195], v[62:65]
	v_mfma_f32_16x16x32_bf16 v[46:49], v[162:165], v[196:199], v[46:49]
	v_mfma_f32_16x16x32_bf16 v[46:49], v[166:169], v[200:203], v[46:49]
	v_mfma_f32_16x16x32_bf16 v[50:53], v[154:157], v[196:199], v[50:53]
	v_mfma_f32_16x16x32_bf16 v[50:53], v[158:161], v[200:203], v[50:53]
	v_mfma_f32_16x16x32_bf16 v[34:37], v[154:157], v[204:207], v[34:37]
	v_mfma_f32_16x16x32_bf16 v[34:37], v[158:161], v[212:215], v[34:37]
	v_mfma_f32_16x16x32_bf16 v[30:33], v[162:165], v[204:207], v[30:33]
	v_mfma_f32_16x16x32_bf16 v[30:33], v[166:169], v[212:215], v[30:33]
	v_mfma_f32_16x16x32_bf16 v[14:17], v[162:165], v[216:219], v[14:17]
	v_mfma_f32_16x16x32_bf16 v[14:17], v[166:169], v[220:223], v[14:17]
	v_mfma_f32_16x16x32_bf16 v[18:21], v[154:157], v[216:219], v[18:21]
	v_mfma_f32_16x16x32_bf16 v[18:21], v[158:161], v[220:223], v[18:21]
	v_mfma_f32_16x16x32_bf16 v[58:61], v[170:173], v[188:191], v[58:61]
	v_mfma_f32_16x16x32_bf16 v[58:61], v[174:177], v[192:195], v[58:61]
	v_mfma_f32_16x16x32_bf16 v[54:57], v[178:181], v[188:191], v[54:57]
	v_mfma_f32_16x16x32_bf16 v[54:57], v[184:187], v[192:195], v[54:57]
	v_mfma_f32_16x16x32_bf16 v[42:45], v[170:173], v[196:199], v[42:45]
	v_mfma_f32_16x16x32_bf16 v[42:45], v[174:177], v[200:203], v[42:45]
	v_mfma_f32_16x16x32_bf16 v[38:41], v[178:181], v[196:199], v[38:41]
	v_mfma_f32_16x16x32_bf16 v[38:41], v[184:187], v[200:203], v[38:41]
	v_mfma_f32_16x16x32_bf16 v[26:29], v[170:173], v[204:207], v[26:29]
	v_mfma_f32_16x16x32_bf16 v[26:29], v[174:177], v[212:215], v[26:29]
	v_mfma_f32_16x16x32_bf16 v[22:25], v[178:181], v[204:207], v[22:25]
	v_mfma_f32_16x16x32_bf16 v[22:25], v[184:187], v[212:215], v[22:25]
	v_mfma_f32_16x16x32_bf16 v[8:11], v[170:173], v[216:219], v[10:13]
	v_mfma_f32_16x16x32_bf16 v[10:13], v[174:177], v[220:223], v[8:11]
	v_mfma_f32_16x16x32_bf16 v[4:7], v[178:181], v[216:219], v[4:7]
	v_mfma_f32_16x16x32_bf16 v[6:9], v[184:187], v[220:223], v[4:7]
	s_barrier
	s_add_u32 s46, s46, 0x100
	s_addc_u32 s47, s47, 0
	s_cmp_ge_i32 s81, s77
	s_cbranch_scc1 .LBB0_2489
	s_mov_b32 s50, s81
	s_branch .LBB0_2485

; #define PG8_STAGE(bufoff, gbase, voff) do { _Pragma("unroll") for (int _i = 0; _i < 2; ++_i) \
;         __builtin_amdgcn_global_load_lds((const unsigned*)((const char*)(gbase) + (voff)[_i]), (PG8_LAS unsigned*)(lds + (bufoff) + ldsw + _i * 8192), 16, 0, 0); } while (0)
; #define PG8_LDA(dst, b, h) do { _Pragma("unroll") for (int m = 0; m < 4; ++m) _Pragma("unroll") for (int k = 0; k < 2; ++k) dst[m][k] = *(const PG8_LAS bf16x8*)(lds + PG8_SA(b, h) + aoff + m * 2048 + k * 1024); } while (0)
; #define PG8_LDB(dst, b, h) do { _Pragma("unroll") for (int n = 0; n < 2; ++n) _Pragma("unroll") for (int k = 0; k < 2; ++k) dst[n][k] = *(const PG8_LAS bf16x8*)(lds + PG8_SB(b, h) + boff + n * 2048 + k * 1024); } while (0)
; #define PG8_MMA(ai, bj, At, Bt) do { __builtin_amdgcn_s_setprio(1); _Pragma("unroll") for (int m = 0; m < 4; ++m) _Pragma("unroll") for (int n = 0; n < 2; ++n) _Pragma("unroll") for (int k = 0; k < 2; ++k) \
;         acc[ai][bj][m][n] = __builtin_amdgcn_mfma_f32_16x16x32_bf16(Bt[n][k], At[m][k], acc[ai][bj][m][n], 0, 0, 0); __builtin_amdgcn_s_setprio(0); } while (0)
; template <class Epi, class Sched, bool ALIGN_EPI = false, bool SP2 = false>
; __device__ __forceinline__ void gemm_phase(PG8_LAS unsigned char* lds, const Gemm g, const Sched& S, const Epi& E) {
;     ...
;         for (int t = 0; t < ntc; t += 2) {
;             if constexpr (Epi::MID) { if (ntc == nt && t == (nt >> 1)) E.mid(acc, cur, wr, wc, fr, fq); }
;             const bool last = (t == ntc - 2);
;             const char* a1 = cA + (size_t)(t + 1) * kstep;
;             const char* a2 = last ? nA : cA + (size_t)(t + 2) * kstep; const char* b2 = last ? nB : cB + (size_t)(t + 2) * kstep;
;             const char* a3 = a2 + kstep; const char* b3 = b2 + kstep;
;             if (last && has_next) S.a_ready(nxt);
;             if constexpr (SP2) {
;             PG8_LDB(B0, 0, 0); PG8_LDB(B1, 0, 1); PG8_SCHED; PG8_LDA(At, 0, 0); PG8_STAGE(PG8_SA(1, 1), a1 + hstep, voffA);
;             PG8_WAIT_V(8); PG8_WAIT_L(0); PG8_BAR; PG8_MMA(0, 0, At, B0); PG8_MMA(0, 1, At, B1); PG8_BAR; PG8_SCHED;
;             PG8_LDA(At, 0, 1); PG8_STAGE(PG8_SB(0, 0), b2, voffB); PG8_STAGE(PG8_SB(0, 1), b2 + hstep, voffB); PG8_STAGE(PG8_SA(0, 0), a2, voffA);
;             PG8_WAIT_V(8); PG8_WAIT_L(0); PG8_BAR; PG8_MMA(1, 0, At, B0); PG8_MMA(1, 1, At, B1); PG8_BAR; PG8_SCHED;
.LBB0_2650:
	ds_read_b128 v[10:13], v195
	ds_read_b128 v[14:17], v195 offset:1024
	ds_read_b128 v[42:45], v195 offset:2048
	ds_read_b128 v[46:49], v195 offset:3072
	ds_read_b128 v[50:53], v238
	ds_read_b128 v[54:57], v238 offset:1024
	ds_read_b128 v[58:61], v238 offset:2048
	ds_read_b128 v[62:65], v238 offset:3072
	s_add_u32 s88, s86, 0xfff00080
	s_addc_u32 s89, s87, -1
	s_cmp_eq_u32 s93, 60
	s_cselect_b32 s91, s19, s89
	s_cselect_b32 s90, s69, s88
	s_cselect_b32 s89, s77, s92
	s_cselect_b32 s88, s79, s85
	s_add_i32 m0, s62, 0xc000
	ds_read_b128 v[66:69], v239
	ds_read_b128 v[70:73], v239 offset:1024
	ds_read_b128 v[170:173], v239 offset:2048
	ds_read_b128 v[174:177], v239 offset:3072
	ds_read_b128 v[178:181], v239 offset:4096
	ds_read_b128 v[208:211], v239 offset:5120
	ds_read_b128 v[212:215], v239 offset:6144
	ds_read_b128 v[216:219], v239 offset:7168
	global_load_lds_dwordx4 v200, s[86:87]
	s_add_i32 m0, s62, 0xe000
	s_nop 0
	global_load_lds_dwordx4 v202, s[86:87]
	s_waitcnt vmcnt(8) lgkmcnt(0)
	s_barrier
	v_mfma_f32_16x16x32_bf16 v[6:9], v[10:13], v[66:69], v[6:9]
	v_mfma_f32_16x16x32_bf16 v[6:9], v[14:17], v[70:73], v[6:9]
	v_mfma_f32_16x16x32_bf16 v[2:5], v[42:45], v[66:69], v[2:5]
	v_mfma_f32_16x16x32_bf16 v[2:5], v[46:49], v[70:73], v[2:5]
	v_mfma_f32_16x16x32_bf16 v[154:157], v[42:45], v[170:173], v[154:157]
	v_mfma_f32_16x16x32_bf16 v[154:157], v[46:49], v[174:177], v[154:157]
	v_mfma_f32_16x16x32_bf16 v[158:161], v[10:13], v[170:173], v[158:161]
	v_mfma_f32_16x16x32_bf16 v[158:161], v[14:17], v[174:177], v[158:161]
	v_mfma_f32_16x16x32_bf16 v[142:145], v[10:13], v[178:181], v[142:145]
	v_mfma_f32_16x16x32_bf16 v[142:145], v[14:17], v[208:211], v[142:145]
	v_mfma_f32_16x16x32_bf16 v[138:141], v[42:45], v[178:181], v[138:141]
	v_mfma_f32_16x16x32_bf16 v[138:141], v[46:49], v[208:211], v[138:141]
	v_mfma_f32_16x16x32_bf16 v[122:125], v[42:45], v[212:215], v[122:125]
	v_mfma_f32_16x16x32_bf16 v[122:125], v[46:49], v[216:219], v[122:125]
	v_mfma_f32_16x16x32_bf16 v[126:129], v[10:13], v[212:215], v[126:129]
	v_mfma_f32_16x16x32_bf16 v[126:129], v[14:17], v[216:219], v[126:129]
	v_mfma_f32_16x16x32_bf16 v[166:169], v[50:53], v[66:69], v[166:169]
	v_mfma_f32_16x16x32_bf16 v[166:169], v[54:57], v[70:73], v[166:169]
	v_mfma_f32_16x16x32_bf16 v[66:69], v[58:61], v[66:69], v[162:165]
	v_mfma_f32_16x16x32_bf16 v[66:69], v[62:65], v[70:73], v[66:69]
	v_mfma_f32_16x16x32_bf16 v[146:149], v[58:61], v[170:173], v[146:149]
	v_mfma_f32_16x16x32_bf16 v[146:149], v[62:65], v[174:177], v[146:149]
	v_mfma_f32_16x16x32_bf16 v[134:137], v[50:53], v[178:181], v[134:137]
	v_mfma_f32_16x16x32_bf16 v[134:137], v[54:57], v[208:211], v[134:137]
	v_mfma_f32_16x16x32_bf16 v[130:133], v[58:61], v[178:181], v[130:133]
	v_mfma_f32_16x16x32_bf16 v[130:133], v[62:65], v[208:211], v[130:133]
	v_mfma_f32_16x16x32_bf16 v[118:121], v[50:53], v[212:215], v[118:121]
	v_mfma_f32_16x16x32_bf16 v[118:121], v[54:57], v[216:219], v[118:121]
	v_mfma_f32_16x16x32_bf16 v[114:117], v[58:61], v[212:215], v[114:117]
	v_mfma_f32_16x16x32_bf16 v[114:117], v[62:65], v[216:219], v[114:117]
	v_mfma_f32_16x16x32_bf16 v[70:73], v[50:53], v[170:173], v[150:153]
	v_mfma_f32_16x16x32_bf16 v[70:73], v[54:57], v[174:177], v[70:73]
	s_barrier
	s_add_i32 vcc_lo, s96, s61
	s_mov_b32 m0, vcc_lo
	ds_read_b128 v[150:153], v239 offset:16384
	ds_read_b128 v[162:165], v239 offset:17408
	ds_read_b128 v[170:173], v239 offset:18432
	ds_read_b128 v[174:177], v239 offset:19456
	ds_read_b128 v[178:181], v239 offset:20480
	ds_read_b128 v[208:211], v239 offset:21504
	ds_read_b128 v[212:215], v239 offset:22528
	ds_read_b128 v[216:219], v239 offset:23552
	global_load_lds_dwordx4 v186, s[88:89]
	s_add_i32 m0, vcc_lo, 0x2000
	s_add_u32 vcc_lo, s88, 0x100000
	s_addc_u32 vcc_hi, s89, 0
	s_add_i32 s58, s70, s61
	global_load_lds_dwordx4 v190, s[88:89]
	s_mov_b32 m0, s58
	s_nop 0
	global_load_lds_dwordx4 v186, vcc
	s_add_i32 m0, s58, 0x2000
	s_nop 0
	global_load_lds_dwordx4 v190, vcc
	s_mov_b32 m0, s62
	s_nop 0
	global_load_lds_dwordx4 v184, s[90:91]
	s_mov_b32 m0, s63
	s_nop 0
	global_load_lds_dwordx4 v188, s[90:91]
	s_waitcnt vmcnt(8) lgkmcnt(0)
	s_barrier
	v_mfma_f32_16x16x32_bf16 v[110:113], v[10:13], v[150:153], v[110:113]
	v_mfma_f32_16x16x32_bf16 v[110:113], v[14:17], v[162:165], v[110:113]
	v_mfma_f32_16x16x32_bf16 v[106:109], v[42:45], v[150:153], v[106:109]
	v_mfma_f32_16x16x32_bf16 v[106:109], v[46:49], v[162:165], v[106:109]
	v_mfma_f32_16x16x32_bf16 v[94:97], v[10:13], v[170:173], v[94:97]
	v_mfma_f32_16x16x32_bf16 v[94:97], v[14:17], v[174:177], v[94:97]
	v_mfma_f32_16x16x32_bf16 v[90:93], v[42:45], v[170:173], v[90:93]
	v_mfma_f32_16x16x32_bf16 v[90:93], v[46:49], v[174:177], v[90:93]
	v_mfma_f32_16x16x32_bf16 v[78:81], v[10:13], v[178:181], v[78:81]
	v_mfma_f32_16x16x32_bf16 v[78:81], v[14:17], v[208:211], v[78:81]
	v_mfma_f32_16x16x32_bf16 v[74:77], v[42:45], v[178:181], v[74:77]
	v_mfma_f32_16x16x32_bf16 v[74:77], v[46:49], v[208:211], v[74:77]
	v_mfma_f32_16x16x32_bf16 v[10:13], v[10:13], v[212:215], v[30:33]
	v_mfma_f32_16x16x32_bf16 v[10:13], v[14:17], v[216:219], v[10:13]
	v_mfma_f32_16x16x32_bf16 v[14:17], v[42:45], v[212:215], v[26:29]
	v_mfma_f32_16x16x32_bf16 v[14:17], v[46:49], v[216:219], v[14:17]
	v_mfma_f32_16x16x32_bf16 v[26:29], v[50:53], v[150:153], v[102:105]
	v_mfma_f32_16x16x32_bf16 v[42:45], v[54:57], v[162:165], v[26:29]
	v_mfma_f32_16x16x32_bf16 v[26:29], v[58:61], v[150:153], v[98:101]
	v_mfma_f32_16x16x32_bf16 v[46:49], v[62:65], v[162:165], v[26:29]
	v_mfma_f32_16x16x32_bf16 v[26:29], v[50:53], v[170:173], v[86:89]
	v_mfma_f32_16x16x32_bf16 v[86:89], v[54:57], v[174:177], v[26:29]
	v_mfma_f32_16x16x32_bf16 v[26:29], v[58:61], v[170:173], v[82:85]
	v_mfma_f32_16x16x32_bf16 v[82:85], v[62:65], v[174:177], v[26:29]
	v_mfma_f32_16x16x32_bf16 v[26:29], v[50:53], v[178:181], v[38:41]
	v_mfma_f32_16x16x32_bf16 v[38:41], v[54:57], v[208:211], v[26:29]
	v_mfma_f32_16x16x32_bf16 v[26:29], v[58:61], v[178:181], v[34:37]
	v_mfma_f32_16x16x32_bf16 v[34:37], v[62:65], v[208:211], v[26:29]
	v_mfma_f32_16x16x32_bf16 v[22:25], v[50:53], v[212:215], v[22:25]
	v_mfma_f32_16x16x32_bf16 v[22:25], v[54:57], v[216:219], v[22:25]
	v_mfma_f32_16x16x32_bf16 v[18:21], v[58:61], v[212:215], v[18:21]
	v_mfma_f32_16x16x32_bf16 v[18:21], v[62:65], v[216:219], v[18:21]
	s_barrier
; #define PG8_STAGE(bufoff, gbase, voff) do { _Pragma("unroll") for (int _i = 0; _i < 2; ++_i) \
;         __builtin_amdgcn_global_load_lds((const unsigned*)((const char*)(gbase) + (voff)[_i]), (PG8_LAS unsigned*)(lds + (bufoff) + ldsw + _i * 8192), 16, 0, 0); } while (0)
; #define PG8_LDA(dst, b, h) do { _Pragma("unroll") for (int m = 0; m < 4; ++m) _Pragma("unroll") for (int k = 0; k < 2; ++k) dst[m][k] = *(const PG8_LAS bf16x8*)(lds + PG8_SA(b, h) + aoff + m * 2048 + k * 1024); } while (0)
; #define PG8_LDB(dst, b, h) do { _Pragma("unroll") for (int n = 0; n < 2; ++n) _Pragma("unroll") for (int k = 0; k < 2; ++k) dst[n][k] = *(const PG8_LAS bf16x8*)(lds + PG8_SB(b, h) + boff + n * 2048 + k * 1024); } while (0)
; #define PG8_MMA(ai, bj, At, Bt) do { __builtin_amdgcn_s_setprio(1); _Pragma("unroll") for (int m = 0; m < 4; ++m) _Pragma("unroll") for (int n = 0; n < 2; ++n) _Pragma("unroll") for (int k = 0; k < 2; ++k) \
;         acc[ai][bj][m][n] = __builtin_amdgcn_mfma_f32_16x16x32_bf16(Bt[n][k], At[m][k], acc[ai][bj][m][n], 0, 0, 0); __builtin_amdgcn_s_setprio(0); } while (0)
; #define PG8_WAIT_V(n) asm volatile("s_waitcnt vmcnt(" #n ")" ::: "memory")
; #define PG8_WAIT_L(n) asm volatile("s_waitcnt lgkmcnt(" #n ")" ::: "memory")
; #define PG8_BAR __builtin_amdgcn_s_barrier()
; #define PG8_SCHED __builtin_amdgcn_sched_barrier(0)
; template <class Epi, class Sched, bool ALIGN_EPI = false, bool SP2 = false>
; __device__ __forceinline__ void gemm_phase(PG8_LAS unsigned char* lds, const Gemm g, const Sched& S, const Epi& E) {
;     ...
;             PG8_LDB(B0, 1, 0); PG8_LDB(B1, 1, 1); PG8_SCHED; PG8_LDA(At, 1, 0); PG8_STAGE(PG8_SA(0, 1), a2 + hstep, voffA);
;             PG8_WAIT_V(8); PG8_WAIT_L(0); PG8_BAR; PG8_MMA(0, 0, At, B0); PG8_MMA(0, 1, At, B1); PG8_BAR; PG8_SCHED;
;             PG8_LDA(At, 1, 1); PG8_STAGE(PG8_SB(1, 0), b3, voffB); PG8_STAGE(PG8_SB(1, 1), b3 + hstep, voffB); PG8_STAGE(PG8_SA(1, 0), a3, voffA);
;             PG8_WAIT_V(8); PG8_WAIT_L(0); PG8_BAR; PG8_MMA(1, 0, At, B0); PG8_MMA(1, 1, At, B1); PG8_BAR; PG8_SCHED;
;     ...
;         if constexpr (ALIGN_EPI) { if (wr == 0) PG8_BAR; }
	s_add_i32 s58, 0, 0x18000
	s_add_i32 s59, 0, 0x1c000
	v_add_u32_e32 v54, s58, v1
	v_add_u32_e32 v98, s59, v1
	ds_read_b128 v[26:29], v54
	ds_read_b128 v[30:33], v54 offset:1024
	ds_read_b128 v[50:53], v54 offset:2048
	ds_read_b128 v[54:57], v54 offset:3072
	ds_read_b128 v[58:61], v98
	ds_read_b128 v[62:65], v98 offset:1024
	ds_read_b128 v[170:173], v98 offset:2048
	ds_read_b128 v[174:177], v98 offset:3072
	s_add_u32 s90, s90, 0x100000
	s_addc_u32 s91, s91, 0
	s_mov_b32 m0, s73
	ds_read_b128 v[98:101], v239 offset:32768
	ds_read_b128 v[102:105], v239 offset:33792
	ds_read_b128 v[178:181], v239 offset:34816
	ds_read_b128 v[208:211], v239 offset:35840
	ds_read_b128 v[212:215], v239 offset:36864
	ds_read_b128 v[216:219], v239 offset:37888
	ds_read_b128 v[220:223], v239 offset:38912
	ds_read_b128 v[224:227], v239 offset:39936
	global_load_lds_dwordx4 v184, s[90:91]
	s_mov_b32 m0, s75
	s_nop 0
	global_load_lds_dwordx4 v188, s[90:91]
	s_waitcnt vmcnt(8) lgkmcnt(0)
	s_barrier
	v_mfma_f32_16x16x32_bf16 v[150:153], v[26:29], v[178:181], v[158:161]
	v_mfma_f32_16x16x32_bf16 v[158:161], v[30:33], v[208:211], v[150:153]
	v_mfma_f32_16x16x32_bf16 v[6:9], v[26:29], v[98:101], v[6:9]
	v_mfma_f32_16x16x32_bf16 v[6:9], v[30:33], v[102:105], v[6:9]
	v_mfma_f32_16x16x32_bf16 v[2:5], v[50:53], v[98:101], v[2:5]
	v_mfma_f32_16x16x32_bf16 v[2:5], v[54:57], v[102:105], v[2:5]
	v_mfma_f32_16x16x32_bf16 v[150:153], v[50:53], v[178:181], v[154:157]
	v_mfma_f32_16x16x32_bf16 v[154:157], v[54:57], v[208:211], v[150:153]
	v_mfma_f32_16x16x32_bf16 v[142:145], v[26:29], v[212:215], v[142:145]
	v_mfma_f32_16x16x32_bf16 v[142:145], v[30:33], v[216:219], v[142:145]
	v_mfma_f32_16x16x32_bf16 v[138:141], v[50:53], v[212:215], v[138:141]
	v_mfma_f32_16x16x32_bf16 v[138:141], v[54:57], v[216:219], v[138:141]
	v_mfma_f32_16x16x32_bf16 v[126:129], v[26:29], v[220:223], v[126:129]
	v_mfma_f32_16x16x32_bf16 v[126:129], v[30:33], v[224:227], v[126:129]
	v_mfma_f32_16x16x32_bf16 v[122:125], v[50:53], v[220:223], v[122:125]
	v_mfma_f32_16x16x32_bf16 v[122:125], v[54:57], v[224:227], v[122:125]
	v_mfma_f32_16x16x32_bf16 v[66:69], v[170:173], v[98:101], v[66:69]
	v_mfma_f32_16x16x32_bf16 v[162:165], v[174:177], v[102:105], v[66:69]
	v_mfma_f32_16x16x32_bf16 v[150:153], v[58:61], v[98:101], v[166:169]
	v_mfma_f32_16x16x32_bf16 v[166:169], v[62:65], v[102:105], v[150:153]
	v_mfma_f32_16x16x32_bf16 v[66:69], v[58:61], v[178:181], v[70:73]
	v_mfma_f32_16x16x32_bf16 v[150:153], v[62:65], v[208:211], v[66:69]
	v_mfma_f32_16x16x32_bf16 v[66:69], v[170:173], v[178:181], v[146:149]
	v_mfma_f32_16x16x32_bf16 v[146:149], v[174:177], v[208:211], v[66:69]
	v_mfma_f32_16x16x32_bf16 v[66:69], v[58:61], v[212:215], v[134:137]
	v_mfma_f32_16x16x32_bf16 v[134:137], v[62:65], v[216:219], v[66:69]
	v_mfma_f32_16x16x32_bf16 v[66:69], v[170:173], v[212:215], v[130:133]
	v_mfma_f32_16x16x32_bf16 v[130:133], v[174:177], v[216:219], v[66:69]
	v_mfma_f32_16x16x32_bf16 v[66:69], v[58:61], v[220:223], v[118:121]
	v_mfma_f32_16x16x32_bf16 v[118:121], v[62:65], v[224:227], v[66:69]
	v_mfma_f32_16x16x32_bf16 v[66:69], v[170:173], v[220:223], v[114:117]
	v_mfma_f32_16x16x32_bf16 v[114:117], v[174:177], v[224:227], v[66:69]
	s_barrier
	s_add_i32 s58, s58, s61
	s_add_u32 s100, s88, 0x80
	s_addc_u32 s101, s89, 0
	s_mov_b32 m0, s58
	s_nop 1
	ds_read_b128 v[66:69], v239 offset:49152
	ds_read_b128 v[70:73], v239 offset:50176
	ds_read_b128 v[178:181], v239 offset:51200
	ds_read_b128 v[208:211], v239 offset:52224
	ds_read_b128 v[212:215], v239 offset:53248
	ds_read_b128 v[216:219], v239 offset:54272
	ds_read_b128 v[220:223], v239 offset:55296
	ds_read_b128 v[224:227], v239 offset:56320
	global_load_lds_dwordx4 v186, s[100:101]
	s_add_i32 m0, s58, 0x2000
	s_add_i32 s58, s59, s61
	global_load_lds_dwordx4 v190, s[100:101]
	s_add_u32 s88, s88, 0x100080
	s_addc_u32 s89, s89, 0
	s_add_u32 s100, s90, 0xfff00080
	s_addc_u32 s101, s91, -1
	s_mov_b32 m0, s58
	s_nop 0
	global_load_lds_dwordx4 v186, s[88:89]
	s_add_i32 m0, s58, 0x2000
	s_nop 0
	global_load_lds_dwordx4 v190, s[88:89]
	s_mov_b32 m0, s29
	s_nop 0
	global_load_lds_dwordx4 v184, s[100:101]
	s_mov_b32 m0, s95
	s_nop 0
	global_load_lds_dwordx4 v188, s[100:101]
	s_waitcnt vmcnt(8) lgkmcnt(0)
	s_barrier
	v_mfma_f32_16x16x32_bf16 v[98:101], v[26:29], v[66:69], v[110:113]
	v_mfma_f32_16x16x32_bf16 v[110:113], v[30:33], v[70:73], v[98:101]
	v_mfma_f32_16x16x32_bf16 v[94:97], v[26:29], v[178:181], v[94:97]
	v_mfma_f32_16x16x32_bf16 v[94:97], v[30:33], v[208:211], v[94:97]
	v_mfma_f32_16x16x32_bf16 v[78:81], v[26:29], v[212:215], v[78:81]
	v_mfma_f32_16x16x32_bf16 v[78:81], v[30:33], v[216:219], v[78:81]
	v_mfma_f32_16x16x32_bf16 v[10:13], v[26:29], v[220:223], v[10:13]
	v_mfma_f32_16x16x32_bf16 v[30:33], v[30:33], v[224:227], v[10:13]
	v_mfma_f32_16x16x32_bf16 v[98:101], v[50:53], v[66:69], v[106:109]
	v_mfma_f32_16x16x32_bf16 v[106:109], v[54:57], v[70:73], v[98:101]
	v_mfma_f32_16x16x32_bf16 v[90:93], v[50:53], v[178:181], v[90:93]
	v_mfma_f32_16x16x32_bf16 v[90:93], v[54:57], v[208:211], v[90:93]
	v_mfma_f32_16x16x32_bf16 v[74:77], v[50:53], v[212:215], v[74:77]
	v_mfma_f32_16x16x32_bf16 v[74:77], v[54:57], v[216:219], v[74:77]
	v_mfma_f32_16x16x32_bf16 v[10:13], v[50:53], v[220:223], v[14:17]
	v_mfma_f32_16x16x32_bf16 v[26:29], v[54:57], v[224:227], v[10:13]
	v_mfma_f32_16x16x32_bf16 v[10:13], v[58:61], v[66:69], v[42:45]
	v_mfma_f32_16x16x32_bf16 v[102:105], v[62:65], v[70:73], v[10:13]
	v_mfma_f32_16x16x32_bf16 v[10:13], v[170:173], v[66:69], v[46:49]
	v_mfma_f32_16x16x32_bf16 v[98:101], v[174:177], v[70:73], v[10:13]
	v_mfma_f32_16x16x32_bf16 v[10:13], v[58:61], v[178:181], v[86:89]
	v_mfma_f32_16x16x32_bf16 v[86:89], v[62:65], v[208:211], v[10:13]
	v_mfma_f32_16x16x32_bf16 v[10:13], v[170:173], v[178:181], v[82:85]
	v_mfma_f32_16x16x32_bf16 v[82:85], v[174:177], v[208:211], v[10:13]
	v_mfma_f32_16x16x32_bf16 v[10:13], v[58:61], v[212:215], v[38:41]
	v_mfma_f32_16x16x32_bf16 v[38:41], v[62:65], v[216:219], v[10:13]
	v_mfma_f32_16x16x32_bf16 v[10:13], v[170:173], v[212:215], v[34:37]
	v_mfma_f32_16x16x32_bf16 v[34:37], v[174:177], v[216:219], v[10:13]
	v_mfma_f32_16x16x32_bf16 v[10:13], v[58:61], v[220:223], v[22:25]
	v_mfma_f32_16x16x32_bf16 v[22:25], v[62:65], v[224:227], v[10:13]
	v_mfma_f32_16x16x32_bf16 v[10:13], v[170:173], v[220:223], v[18:21]
	v_mfma_f32_16x16x32_bf16 v[18:21], v[174:177], v[224:227], v[10:13]
	s_barrier
	s_add_i32 s93, s93, 2
	s_add_u32 s86, s86, 0x100
	s_addc_u32 s87, s87, 0
	s_add_u32 s85, s85, 0x100
	s_addc_u32 s92, s92, 0
	s_cmp_gt_u32 s93, 61
	s_cbranch_scc0 .LBB0_2650
	s_and_b64 vcc, exec, s[42:43]
	s_cbranch_vccz .LBB0_2653
	s_barrier

; #define PG8_STAGE(bufoff, gbase, voff) do { _Pragma("unroll") for (int _i = 0; _i < 2; ++_i) \
;         __builtin_amdgcn_global_load_lds((const unsigned*)((const char*)(gbase) + (voff)[_i]), (PG8_LAS unsigned*)(lds + (bufoff) + ldsw + _i * 8192), 16, 0, 0); } while (0)
; #define PG8_LDA(dst, b, h) do { _Pragma("unroll") for (int m = 0; m < 4; ++m) _Pragma("unroll") for (int k = 0; k < 2; ++k) dst[m][k] = *(const PG8_LAS bf16x8*)(lds + PG8_SA(b, h) + aoff + m * 2048 + k * 1024); } while (0)
; #define PG8_LDB(dst, b, h) do { _Pragma("unroll") for (int n = 0; n < 2; ++n) _Pragma("unroll") for (int k = 0; k < 2; ++k) dst[n][k] = *(const PG8_LAS bf16x8*)(lds + PG8_SB(b, h) + boff + n * 2048 + k * 1024); } while (0)
; #define PG8_MMA(ai, bj, At, Bt) do { __builtin_amdgcn_s_setprio(1); _Pragma("unroll") for (int m = 0; m < 4; ++m) _Pragma("unroll") for (int n = 0; n < 2; ++n) _Pragma("unroll") for (int k = 0; k < 2; ++k) \
;         acc[ai][bj][m][n] = __builtin_amdgcn_mfma_f32_16x16x32_bf16(Bt[n][k], At[m][k], acc[ai][bj][m][n], 0, 0, 0); __builtin_amdgcn_s_setprio(0); } while (0)
; #define PG8_WAIT_V(n) asm volatile("s_waitcnt vmcnt(" #n ")" ::: "memory")
; #define PG8_WAIT_L(n) asm volatile("s_waitcnt lgkmcnt(" #n ")" ::: "memory")
; template <class Epi, class Sched, bool ALIGN_EPI = false, bool SP2 = false>
; __device__ __forceinline__ void gemm_phase(PG8_LAS unsigned char* lds, const Gemm g, const Sched& S, const Epi& E) {
;     ...
;             const bool last = (t == ntc - 2);
;             const char* a1 = cA + (size_t)(t + 1) * kstep;
;             const char* a2 = last ? nA : cA + (size_t)(t + 2) * kstep; const char* b2 = last ? nB : cB + (size_t)(t + 2) * kstep;
;             const char* a3 = a2 + kstep; const char* b3 = b2 + kstep;
;             if (last && has_next) S.a_ready(nxt);
;             if constexpr (SP2) {
;             PG8_LDB(B0, 0, 0); PG8_LDB(B1, 0, 1); PG8_SCHED; PG8_LDA(At, 0, 0); PG8_STAGE(PG8_SA(1, 1), a1 + hstep, voffA);
;             PG8_WAIT_V(8); PG8_WAIT_L(0); PG8_BAR; PG8_MMA(0, 0, At, B0); PG8_MMA(0, 1, At, B1); PG8_BAR; PG8_SCHED;
;             PG8_LDA(At, 0, 1); PG8_STAGE(PG8_SB(0, 0), b2, voffB); PG8_STAGE(PG8_SB(0, 1), b2 + hstep, voffB); PG8_STAGE(PG8_SA(0, 0), a2, voffA);
;             PG8_WAIT_V(8); PG8_WAIT_L(0); PG8_BAR; PG8_MMA(1, 0, At, B0); PG8_MMA(1, 1, At, B1); PG8_BAR; PG8_SCHED;
.LBB0_3522:
	ds_read_b128 v[144:147], v177
	ds_read_b128 v[148:151], v177 offset:1024
	ds_read_b128 v[152:155], v177 offset:2048
	ds_read_b128 v[156:159], v177 offset:3072
	ds_read_b128 v[160:163], v178
	ds_read_b128 v[164:167], v178 offset:1024
	ds_read_b128 v[168:171], v178 offset:2048
	ds_read_b128 v[172:175], v178 offset:3072
	s_add_u32 s40, s38, 0x100
	s_addc_u32 s41, s39, 0
	s_cmp_eq_u32 s69, s71
	s_cselect_b32 s45, s35, s41
	s_cselect_b32 s44, s34, s40
	s_cselect_b32 s43, s37, s70
	s_cselect_b32 s42, s36, s31
	s_add_i32 m0, s51, 0xc000
	ds_read_b128 v[180:183], v179
	ds_read_b128 v[184:187], v179 offset:1024
	ds_read_b128 v[188:191], v179 offset:2048
	ds_read_b128 v[192:195], v179 offset:3072
	ds_read_b128 v[196:199], v179 offset:4096
	ds_read_b128 v[200:203], v179 offset:5120
	ds_read_b128 v[204:207], v179 offset:6144
	ds_read_b128 v[208:211], v179 offset:7168
	global_load_lds_dwordx4 v138, s[38:39]
	s_add_i32 m0, s51, 0xe000
	s_nop 0
	global_load_lds_dwordx4 v140, s[38:39]
	s_waitcnt vmcnt(8) lgkmcnt(0)
	s_barrier
	v_mfma_f32_16x16x32_bf16 v[126:129], v[144:147], v[180:183], v[126:129]
	v_mfma_f32_16x16x32_bf16 v[126:129], v[148:151], v[184:187], v[126:129]
	v_mfma_f32_16x16x32_bf16 v[122:125], v[152:155], v[180:183], v[122:125]
	v_mfma_f32_16x16x32_bf16 v[122:125], v[156:159], v[184:187], v[122:125]
	v_mfma_f32_16x16x32_bf16 v[106:109], v[152:155], v[188:191], v[106:109]
	v_mfma_f32_16x16x32_bf16 v[106:109], v[156:159], v[192:195], v[106:109]
	v_mfma_f32_16x16x32_bf16 v[110:113], v[144:147], v[188:191], v[110:113]
	v_mfma_f32_16x16x32_bf16 v[110:113], v[148:151], v[192:195], v[110:113]
	v_mfma_f32_16x16x32_bf16 v[94:97], v[144:147], v[196:199], v[94:97]
	v_mfma_f32_16x16x32_bf16 v[94:97], v[148:151], v[200:203], v[94:97]
	v_mfma_f32_16x16x32_bf16 v[90:93], v[152:155], v[196:199], v[90:93]
	v_mfma_f32_16x16x32_bf16 v[90:93], v[156:159], v[200:203], v[90:93]
	v_mfma_f32_16x16x32_bf16 v[74:77], v[152:155], v[204:207], v[74:77]
	v_mfma_f32_16x16x32_bf16 v[74:77], v[156:159], v[208:211], v[74:77]
	v_mfma_f32_16x16x32_bf16 v[78:81], v[144:147], v[204:207], v[78:81]
	v_mfma_f32_16x16x32_bf16 v[78:81], v[148:151], v[208:211], v[78:81]
	v_mfma_f32_16x16x32_bf16 v[118:121], v[160:163], v[180:183], v[118:121]
	v_mfma_f32_16x16x32_bf16 v[118:121], v[164:167], v[184:187], v[118:121]
	v_mfma_f32_16x16x32_bf16 v[114:117], v[168:171], v[180:183], v[114:117]
	v_mfma_f32_16x16x32_bf16 v[114:117], v[172:175], v[184:187], v[114:117]
	v_mfma_f32_16x16x32_bf16 v[98:101], v[168:171], v[188:191], v[98:101]
	v_mfma_f32_16x16x32_bf16 v[98:101], v[172:175], v[192:195], v[98:101]
	v_mfma_f32_16x16x32_bf16 v[102:105], v[160:163], v[188:191], v[102:105]
	v_mfma_f32_16x16x32_bf16 v[102:105], v[164:167], v[192:195], v[102:105]
	v_mfma_f32_16x16x32_bf16 v[86:89], v[160:163], v[196:199], v[86:89]
	v_mfma_f32_16x16x32_bf16 v[86:89], v[164:167], v[200:203], v[86:89]
	v_mfma_f32_16x16x32_bf16 v[82:85], v[168:171], v[196:199], v[82:85]
	v_mfma_f32_16x16x32_bf16 v[82:85], v[172:175], v[200:203], v[82:85]
	v_mfma_f32_16x16x32_bf16 v[66:69], v[168:171], v[204:207], v[66:69]
	v_mfma_f32_16x16x32_bf16 v[66:69], v[172:175], v[208:211], v[66:69]
	v_mfma_f32_16x16x32_bf16 v[70:73], v[160:163], v[204:207], v[70:73]
	v_mfma_f32_16x16x32_bf16 v[70:73], v[164:167], v[208:211], v[70:73]
	s_barrier
	s_add_i32 s38, s63, s50
	s_mov_b32 m0, s38
	ds_read_b128 v[180:183], v179 offset:16384
	ds_read_b128 v[184:187], v179 offset:17408
	ds_read_b128 v[188:191], v179 offset:18432
	ds_read_b128 v[192:195], v179 offset:19456
	ds_read_b128 v[196:199], v179 offset:20480
	ds_read_b128 v[200:203], v179 offset:21504
	ds_read_b128 v[204:207], v179 offset:22528
	ds_read_b128 v[208:211], v179 offset:23552
	global_load_lds_dwordx4 v130, s[42:43]
	s_add_i32 m0, s38, 0x2000
	s_add_u32 s38, s42, 0x300000
	s_addc_u32 s39, s43, 0
	s_add_i32 s58, s64, s50
	global_load_lds_dwordx4 v132, s[42:43]
	s_mov_b32 m0, s58
	s_nop 0
	global_load_lds_dwordx4 v130, s[38:39]
	s_add_i32 m0, s58, 0x2000
	s_nop 0
	global_load_lds_dwordx4 v132, s[38:39]
	s_mov_b32 m0, s51
	s_nop 0
	global_load_lds_dwordx4 v130, s[44:45]
	s_mov_b32 m0, s52
	s_nop 0
	global_load_lds_dwordx4 v132, s[44:45]
	s_waitcnt vmcnt(8) lgkmcnt(0)
	s_barrier
	v_mfma_f32_16x16x32_bf16 v[62:65], v[144:147], v[180:183], v[62:65]
	v_mfma_f32_16x16x32_bf16 v[62:65], v[148:151], v[184:187], v[62:65]
	v_mfma_f32_16x16x32_bf16 v[58:61], v[152:155], v[180:183], v[58:61]
	v_mfma_f32_16x16x32_bf16 v[58:61], v[156:159], v[184:187], v[58:61]
	v_mfma_f32_16x16x32_bf16 v[42:45], v[152:155], v[188:191], v[42:45]
	v_mfma_f32_16x16x32_bf16 v[42:45], v[156:159], v[192:195], v[42:45]
	v_mfma_f32_16x16x32_bf16 v[46:49], v[144:147], v[188:191], v[46:49]
	v_mfma_f32_16x16x32_bf16 v[46:49], v[148:151], v[192:195], v[46:49]
	v_mfma_f32_16x16x32_bf16 v[30:33], v[144:147], v[196:199], v[30:33]
	v_mfma_f32_16x16x32_bf16 v[30:33], v[148:151], v[200:203], v[30:33]
	v_mfma_f32_16x16x32_bf16 v[26:29], v[152:155], v[196:199], v[26:29]
	v_mfma_f32_16x16x32_bf16 v[26:29], v[156:159], v[200:203], v[26:29]
	v_mfma_f32_16x16x32_bf16 v[10:13], v[152:155], v[204:207], v[10:13]
	v_mfma_f32_16x16x32_bf16 v[10:13], v[156:159], v[208:211], v[10:13]
	v_mfma_f32_16x16x32_bf16 v[14:17], v[144:147], v[204:207], v[14:17]
	v_mfma_f32_16x16x32_bf16 v[14:17], v[148:151], v[208:211], v[14:17]
	v_mfma_f32_16x16x32_bf16 v[54:57], v[160:163], v[180:183], v[54:57]
	v_mfma_f32_16x16x32_bf16 v[54:57], v[164:167], v[184:187], v[54:57]
	v_mfma_f32_16x16x32_bf16 v[50:53], v[168:171], v[180:183], v[50:53]
	v_mfma_f32_16x16x32_bf16 v[50:53], v[172:175], v[184:187], v[50:53]
	v_mfma_f32_16x16x32_bf16 v[34:37], v[168:171], v[188:191], v[34:37]
	v_mfma_f32_16x16x32_bf16 v[34:37], v[172:175], v[192:195], v[34:37]
	v_mfma_f32_16x16x32_bf16 v[38:41], v[160:163], v[188:191], v[38:41]
	v_mfma_f32_16x16x32_bf16 v[38:41], v[164:167], v[192:195], v[38:41]
	v_mfma_f32_16x16x32_bf16 v[22:25], v[160:163], v[196:199], v[22:25]
	v_mfma_f32_16x16x32_bf16 v[22:25], v[164:167], v[200:203], v[22:25]
	v_mfma_f32_16x16x32_bf16 v[18:21], v[168:171], v[196:199], v[18:21]
	v_mfma_f32_16x16x32_bf16 v[18:21], v[172:175], v[200:203], v[18:21]
	v_mfma_f32_16x16x32_bf16 v[2:5], v[168:171], v[204:207], v[2:5]
	v_mfma_f32_16x16x32_bf16 v[2:5], v[172:175], v[208:211], v[2:5]
	v_mfma_f32_16x16x32_bf16 v[6:9], v[160:163], v[204:207], v[6:9]
	v_mfma_f32_16x16x32_bf16 v[6:9], v[164:167], v[208:211], v[6:9]
	s_barrier
; #define PG8_STAGE(bufoff, gbase, voff) do { _Pragma("unroll") for (int _i = 0; _i < 2; ++_i) \
;         __builtin_amdgcn_global_load_lds((const unsigned*)((const char*)(gbase) + (voff)[_i]), (PG8_LAS unsigned*)(lds + (bufoff) + ldsw + _i * 8192), 16, 0, 0); } while (0)
; #define PG8_LDA(dst, b, h) do { _Pragma("unroll") for (int m = 0; m < 4; ++m) _Pragma("unroll") for (int k = 0; k < 2; ++k) dst[m][k] = *(const PG8_LAS bf16x8*)(lds + PG8_SA(b, h) + aoff + m * 2048 + k * 1024); } while (0)
; #define PG8_LDB(dst, b, h) do { _Pragma("unroll") for (int n = 0; n < 2; ++n) _Pragma("unroll") for (int k = 0; k < 2; ++k) dst[n][k] = *(const PG8_LAS bf16x8*)(lds + PG8_SB(b, h) + boff + n * 2048 + k * 1024); } while (0)
; #define PG8_MMA(ai, bj, At, Bt) do { __builtin_amdgcn_s_setprio(1); _Pragma("unroll") for (int m = 0; m < 4; ++m) _Pragma("unroll") for (int n = 0; n < 2; ++n) _Pragma("unroll") for (int k = 0; k < 2; ++k) \
;         acc[ai][bj][m][n] = __builtin_amdgcn_mfma_f32_16x16x32_bf16(Bt[n][k], At[m][k], acc[ai][bj][m][n], 0, 0, 0); __builtin_amdgcn_s_setprio(0); } while (0)
; #define PG8_WAIT_V(n) asm volatile("s_waitcnt vmcnt(" #n ")" ::: "memory")
; #define PG8_WAIT_L(n) asm volatile("s_waitcnt lgkmcnt(" #n ")" ::: "memory")
; #define PG8_BAR __builtin_amdgcn_s_barrier()
; #define PG8_SCHED __builtin_amdgcn_sched_barrier(0)
;     __device__ __forceinline__ void operator()(const f32x4 (&acc)[2][2][4][2], const Unit& u, int wr, int wc, int fr, int fq) const {
;     ...
;         if (u.ntu != 192) {
; template <class Epi, class Sched, bool ALIGN_EPI = false, bool SP2 = false>
; __device__ __forceinline__ void gemm_phase(PG8_LAS unsigned char* lds, const Gemm g, const Sched& S, const Epi& E) {
;     ...
;             PG8_LDB(B0, 1, 0); PG8_LDB(B1, 1, 1); PG8_SCHED; PG8_LDA(At, 1, 0); PG8_STAGE(PG8_SA(0, 1), a2 + hstep, voffA);
;             PG8_WAIT_V(8); PG8_WAIT_L(0); PG8_BAR; PG8_MMA(0, 0, At, B0); PG8_MMA(0, 1, At, B1); PG8_BAR; PG8_SCHED;
;             PG8_LDA(At, 1, 1); PG8_STAGE(PG8_SB(1, 0), b3, voffB); PG8_STAGE(PG8_SB(1, 1), b3 + hstep, voffB); PG8_STAGE(PG8_SA(1, 0), a3, voffA);
;             PG8_WAIT_V(8); PG8_WAIT_L(0); PG8_BAR; PG8_MMA(1, 0, At, B0); PG8_MMA(1, 1, At, B1); PG8_BAR; PG8_SCHED;
	s_add_i32 s58, 0, 0x18000
	v_add_u32_e32 v134, s58, v1
	s_add_i32 s59, 0, 0x1c000
	ds_read_b128 v[144:147], v134
	ds_read_b128 v[148:151], v134 offset:1024
	ds_read_b128 v[152:155], v134 offset:2048
	ds_read_b128 v[156:159], v134 offset:3072
	v_add_u32_e32 v134, s59, v1
	ds_read_b128 v[160:163], v134
	ds_read_b128 v[164:167], v134 offset:1024
	ds_read_b128 v[168:171], v134 offset:2048
	ds_read_b128 v[172:175], v134 offset:3072
	s_add_u32 s38, s44, 0x300000
	s_addc_u32 s39, s45, 0
	s_mov_b32 m0, s53
	ds_read_b128 v[180:183], v179 offset:32768
	ds_read_b128 v[184:187], v179 offset:33792
	ds_read_b128 v[188:191], v179 offset:34816
	ds_read_b128 v[192:195], v179 offset:35840
	ds_read_b128 v[196:199], v179 offset:36864
	ds_read_b128 v[200:203], v179 offset:37888
	ds_read_b128 v[204:207], v179 offset:38912
	ds_read_b128 v[208:211], v179 offset:39936
	global_load_lds_dwordx4 v130, s[38:39]
	s_mov_b32 m0, s54
	s_nop 0
	global_load_lds_dwordx4 v132, s[38:39]
	s_waitcnt vmcnt(8) lgkmcnt(0)
	s_barrier
	v_mfma_f32_16x16x32_bf16 v[126:129], v[144:147], v[180:183], v[126:129]
	v_mfma_f32_16x16x32_bf16 v[126:129], v[148:151], v[184:187], v[126:129]
	v_mfma_f32_16x16x32_bf16 v[122:125], v[152:155], v[180:183], v[122:125]
	v_mfma_f32_16x16x32_bf16 v[122:125], v[156:159], v[184:187], v[122:125]
	v_mfma_f32_16x16x32_bf16 v[106:109], v[152:155], v[188:191], v[106:109]
	v_mfma_f32_16x16x32_bf16 v[106:109], v[156:159], v[192:195], v[106:109]
	v_mfma_f32_16x16x32_bf16 v[110:113], v[144:147], v[188:191], v[110:113]
	v_mfma_f32_16x16x32_bf16 v[110:113], v[148:151], v[192:195], v[110:113]
	v_mfma_f32_16x16x32_bf16 v[94:97], v[144:147], v[196:199], v[94:97]
	v_mfma_f32_16x16x32_bf16 v[94:97], v[148:151], v[200:203], v[94:97]
	v_mfma_f32_16x16x32_bf16 v[90:93], v[152:155], v[196:199], v[90:93]
	v_mfma_f32_16x16x32_bf16 v[90:93], v[156:159], v[200:203], v[90:93]
	v_mfma_f32_16x16x32_bf16 v[74:77], v[152:155], v[204:207], v[74:77]
	v_mfma_f32_16x16x32_bf16 v[74:77], v[156:159], v[208:211], v[74:77]
	v_mfma_f32_16x16x32_bf16 v[78:81], v[144:147], v[204:207], v[78:81]
	v_mfma_f32_16x16x32_bf16 v[78:81], v[148:151], v[208:211], v[78:81]
	v_mfma_f32_16x16x32_bf16 v[118:121], v[160:163], v[180:183], v[118:121]
	v_mfma_f32_16x16x32_bf16 v[118:121], v[164:167], v[184:187], v[118:121]
	v_mfma_f32_16x16x32_bf16 v[114:117], v[168:171], v[180:183], v[114:117]
	v_mfma_f32_16x16x32_bf16 v[114:117], v[172:175], v[184:187], v[114:117]
	v_mfma_f32_16x16x32_bf16 v[98:101], v[168:171], v[188:191], v[98:101]
	v_mfma_f32_16x16x32_bf16 v[98:101], v[172:175], v[192:195], v[98:101]
	v_mfma_f32_16x16x32_bf16 v[102:105], v[160:163], v[188:191], v[102:105]
	v_mfma_f32_16x16x32_bf16 v[102:105], v[164:167], v[192:195], v[102:105]
	v_mfma_f32_16x16x32_bf16 v[86:89], v[160:163], v[196:199], v[86:89]
	v_mfma_f32_16x16x32_bf16 v[86:89], v[164:167], v[200:203], v[86:89]
	v_mfma_f32_16x16x32_bf16 v[82:85], v[168:171], v[196:199], v[82:85]
	v_mfma_f32_16x16x32_bf16 v[82:85], v[172:175], v[200:203], v[82:85]
	v_mfma_f32_16x16x32_bf16 v[66:69], v[168:171], v[204:207], v[66:69]
	v_mfma_f32_16x16x32_bf16 v[66:69], v[172:175], v[208:211], v[66:69]
	v_mfma_f32_16x16x32_bf16 v[70:73], v[160:163], v[204:207], v[70:73]
	v_mfma_f32_16x16x32_bf16 v[70:73], v[164:167], v[208:211], v[70:73]
	s_barrier
	s_add_i32 s38, s58, s50
	s_add_u32 s98, s42, 0x80
	s_addc_u32 s99, s43, 0
	s_add_u32 s100, s44, 0x80
	s_addc_u32 s101, s45, 0
	s_mov_b32 m0, s38
	ds_read_b128 v[180:183], v179 offset:49152
	ds_read_b128 v[184:187], v179 offset:50176
	ds_read_b128 v[188:191], v179 offset:51200
	ds_read_b128 v[192:195], v179 offset:52224
	ds_read_b128 v[196:199], v179 offset:53248
	ds_read_b128 v[200:203], v179 offset:54272
	ds_read_b128 v[204:207], v179 offset:55296
	ds_read_b128 v[208:211], v179 offset:56320
	global_load_lds_dwordx4 v130, s[98:99]
	s_add_i32 m0, s38, 0x2000
	s_add_u32 s38, s42, 0x300080
	s_addc_u32 s39, s43, 0
	s_add_i32 s42, s59, s50
	global_load_lds_dwordx4 v132, s[98:99]
	s_mov_b32 m0, s42
	s_nop 0
	global_load_lds_dwordx4 v130, s[38:39]
	s_add_i32 m0, s42, 0x2000
	s_nop 0
	global_load_lds_dwordx4 v132, s[38:39]
	s_mov_b32 m0, s57
	s_nop 0
	global_load_lds_dwordx4 v130, s[100:101]
	s_mov_b32 m0, s60
	s_nop 0
	global_load_lds_dwordx4 v132, s[100:101]
	s_waitcnt vmcnt(8) lgkmcnt(0)
	s_barrier
	v_mfma_f32_16x16x32_bf16 v[62:65], v[144:147], v[180:183], v[62:65]
	v_mfma_f32_16x16x32_bf16 v[62:65], v[148:151], v[184:187], v[62:65]
	v_mfma_f32_16x16x32_bf16 v[58:61], v[152:155], v[180:183], v[58:61]
	v_mfma_f32_16x16x32_bf16 v[58:61], v[156:159], v[184:187], v[58:61]
	v_mfma_f32_16x16x32_bf16 v[42:45], v[152:155], v[188:191], v[42:45]
	v_mfma_f32_16x16x32_bf16 v[42:45], v[156:159], v[192:195], v[42:45]
	v_mfma_f32_16x16x32_bf16 v[46:49], v[144:147], v[188:191], v[46:49]
	v_mfma_f32_16x16x32_bf16 v[46:49], v[148:151], v[192:195], v[46:49]
	v_mfma_f32_16x16x32_bf16 v[30:33], v[144:147], v[196:199], v[30:33]
	v_mfma_f32_16x16x32_bf16 v[30:33], v[148:151], v[200:203], v[30:33]
	v_mfma_f32_16x16x32_bf16 v[26:29], v[152:155], v[196:199], v[26:29]
	v_mfma_f32_16x16x32_bf16 v[26:29], v[156:159], v[200:203], v[26:29]
	v_mfma_f32_16x16x32_bf16 v[10:13], v[152:155], v[204:207], v[10:13]
	v_mfma_f32_16x16x32_bf16 v[10:13], v[156:159], v[208:211], v[10:13]
	v_mfma_f32_16x16x32_bf16 v[14:17], v[144:147], v[204:207], v[14:17]
	v_mfma_f32_16x16x32_bf16 v[14:17], v[148:151], v[208:211], v[14:17]
	v_mfma_f32_16x16x32_bf16 v[54:57], v[160:163], v[180:183], v[54:57]
	v_mfma_f32_16x16x32_bf16 v[54:57], v[164:167], v[184:187], v[54:57]
	v_mfma_f32_16x16x32_bf16 v[50:53], v[168:171], v[180:183], v[50:53]
	v_mfma_f32_16x16x32_bf16 v[50:53], v[172:175], v[184:187], v[50:53]
	v_mfma_f32_16x16x32_bf16 v[34:37], v[168:171], v[188:191], v[34:37]
	v_mfma_f32_16x16x32_bf16 v[34:37], v[172:175], v[192:195], v[34:37]
	v_mfma_f32_16x16x32_bf16 v[38:41], v[160:163], v[188:191], v[38:41]
	v_mfma_f32_16x16x32_bf16 v[38:41], v[164:167], v[192:195], v[38:41]
	v_mfma_f32_16x16x32_bf16 v[22:25], v[160:163], v[196:199], v[22:25]
	v_mfma_f32_16x16x32_bf16 v[22:25], v[164:167], v[200:203], v[22:25]
	v_mfma_f32_16x16x32_bf16 v[18:21], v[168:171], v[196:199], v[18:21]
	v_mfma_f32_16x16x32_bf16 v[18:21], v[172:175], v[200:203], v[18:21]
	v_mfma_f32_16x16x32_bf16 v[2:5], v[168:171], v[204:207], v[2:5]
	v_mfma_f32_16x16x32_bf16 v[2:5], v[172:175], v[208:211], v[2:5]
	v_mfma_f32_16x16x32_bf16 v[6:9], v[160:163], v[204:207], v[6:9]
	v_mfma_f32_16x16x32_bf16 v[6:9], v[164:167], v[208:211], v[6:9]
	s_barrier
	s_add_i32 s42, s71, 2
	s_add_u32 s31, s31, 0x100
	s_addc_u32 s70, s70, 0
	s_cmp_ge_i32 s71, s69
	s_mov_b64 s[38:39], s[40:41]
	s_mov_b32 s71, s42
	s_cbranch_scc0 .LBB0_3522
	s_and_b64 vcc, exec, s[20:21]
	s_cbranch_vccz .LBB0_3543
	s_barrier
	v_lshl_or_b32 v144, s5, 8, v176
	s_cmpk_eq_i32 s69, 0xc0
	s_mov_b64 s[38:39], -1
	s_cbranch_scc0 .LBB0_3544
